# k1 + attention v_pk_fma_f32 (scalar-broadcast) split into two v_fma_f32
# speedup vs baseline: 1.0002x; 1.0002x over previous
.LBB0_532:
	s_or_b64 exec, exec, s[4:5]
	v_ashrrev_i32_e32 v237, 6, v0
	v_and_b32_e32 v238, 31, v0
	v_and_b32_e32 v1, 0x3fffffc0, v0
	s_add_i32 s4, 0, 0x10000
	v_lshlrev_b32_e32 v234, 5, v237
	v_lshl_add_u32 v239, v1, 2, s4
	v_or_b32_e32 v1, v234, v238
	v_add_u32_e32 v2, s30, v1
	v_ashrrev_i32_e32 v3, 31, v2
	v_mul_lo_u32 v4, s40, v3
	v_mul_lo_u32 v5, s41, v2
	v_mad_u64_u32 v[2:3], s[4:5], s40, v2, 0
	v_bfe_u32 v236, v0, 5, 1
	v_add3_u32 v3, v3, v4, v5
	v_lshl_add_u64 v[2:3], v[2:3], 1, s[88:89]
	v_lshlrev_b32_e32 v144, 4, v236
	v_lshl_add_u64 v[2:3], v[2:3], 0, v[144:145]
	v_ashrrev_i32_e32 v220, 4, v0
	global_load_dwordx4 v[174:177], v[2:3], off
	global_load_dwordx4 v[170:173], v[2:3], off offset:32
	global_load_dwordx4 v[166:169], v[2:3], off offset:64
	global_load_dwordx4 v[162:165], v[2:3], off offset:96
	global_load_dwordx4 v[158:161], v[2:3], off offset:128
	global_load_dwordx4 v[154:157], v[2:3], off offset:160
	global_load_dwordx4 v[150:153], v[2:3], off offset:192
	global_load_dwordx4 v[146:149], v[2:3], off offset:224
	v_and_b32_e32 v3, 0xfffff0, v220
	v_lshlrev_b32_e32 v4, 1, v220
	v_add_u32_e32 v241, s28, v1
	v_lshlrev_b32_e32 v1, 3, v0
	v_and_or_b32 v3, v4, 8, v3
	v_and_b32_e32 v2, 0x78, v1
	v_lshrrev_b32_e32 v4, 1, v220
	v_lshrrev_b32_e32 v3, 1, v3
	v_bfe_u32 v1, v1, 5, 2
	v_and_b32_e32 v5, 3, v220
	v_or_b32_e32 v3, v3, v1
	v_and_or_b32 v4, v4, 4, v5
	v_lshlrev_b32_e32 v48, 1, v2
	v_lshlrev_b32_e32 v3, 9, v3
	v_lshlrev_b32_e32 v4, 6, v4
	v_and_b32_e32 v2, 48, v48
	v_add_u32_e32 v19, 32, v220
	v_or3_b32 v18, v3, v4, v2
	v_and_b32_e32 v3, 0xfffff0, v19
	v_lshlrev_b32_e32 v5, 1, v19
	v_and_or_b32 v3, v5, 8, v3
	v_lshrrev_b32_e32 v3, 1, v3
	v_or_b32_e32 v1, v3, v1
	v_and_b32_e32 v233, 63, v0
	v_lshlrev_b32_e32 v1, 9, v1
	v_lshlrev_b32_e32 v235, 4, v0
	v_or3_b32 v1, v1, v4, v2
	v_lshlrev_b32_e32 v2, 3, v233
	v_and_b32_e32 v3, 0xc0, v235
	v_lshlrev_b32_e32 v4, 1, v0
	s_cmp_lg_u32 0, -1
	v_ashrrev_i32_e32 v221, 31, v220
	v_and_or_b32 v3, v2, 24, v3
	v_and_b32_e32 v4, 32, v4
	v_and_b32_e32 v2, 0x100, v2
	s_cselect_b32 s6, 0, 0
	s_ashr_i32 s83, s82, 31
	v_lshl_add_u64 v[222:223], v[220:221], 0, 32
	v_or3_b32 v50, v3, v4, v2
	v_lshl_add_u64 v[2:3], v[220:221], 0, s[82:83]
	v_lshl_add_u64 v[6:7], v[222:223], 0, s[82:83]
	v_mul_lo_u32 v4, v3, s40
	v_mul_lo_u32 v5, v2, s41
	v_mad_u64_u32 v[2:3], s[8:9], v2, s40, 0
	v_mul_lo_u32 v8, v7, s40
	v_mul_lo_u32 v9, v6, s41
	v_mad_u64_u32 v[6:7], s[8:9], v6, s40, 0
	v_add3_u32 v3, v3, v5, v4
	v_add3_u32 v7, v7, v9, v8
	v_lshlrev_b64 v[10:11], 1, v[2:3]
	v_lshlrev_b64 v[14:15], 1, v[6:7]
	v_lshl_add_u64 v[2:3], s[80:81], 0, v[10:11]
	v_mov_b32_e32 v49, v145
	v_lshl_add_u64 v[6:7], s[80:81], 0, v[14:15]
	v_lshl_add_u64 v[10:11], s[78:79], 0, v[10:11]
	v_lshl_add_u64 v[14:15], s[78:79], 0, v[14:15]
	v_lshl_add_u64 v[2:3], v[2:3], 0, v[48:49]
	v_lshl_add_u64 v[6:7], v[6:7], 0, v[48:49]
	v_lshl_add_u64 v[10:11], v[10:11], 0, v[48:49]
	v_lshl_add_u64 v[14:15], v[14:15], 0, v[48:49]
	global_load_dwordx4 v[2:5], v[2:3], off
	v_add_u32_e32 v248, 0, v1
	global_load_dwordx4 v[6:9], v[6:7], off
	v_lshlrev_b32_e32 v1, 8, v220
	global_load_dwordx4 v[10:13], v[10:11], off
	v_and_b32_e32 v0, 0x70, v0
	global_load_dwordx4 v[14:17], v[14:15], off
	v_bitop3_b32 v1, v48, v1, v0 bitop3:0xde
	v_add_u32_e32 v250, 0, v1
	v_lshlrev_b32_e32 v1, 8, v19
	v_bitop3_b32 v0, v48, v1, v0 bitop3:0xde
	v_lshlrev_b32_e32 v51, 8, v238
	v_and_b32_e32 v60, 0x70, v235
	v_add_u32_e32 v251, 0, v0
	v_bitop3_b32 v0, v144, v51, v60 bitop3:0xde
	v_add_u32_e32 v247, 0, v18
	v_add_u32_e32 v249, 0, v0
	s_waitcnt vmcnt(0)
	v_or_b32_e32 v52, 32, v144
	v_bitop3_b32 v52, v52, v51, v60 bitop3:0xde
	v_add_u32_e32 v252, 0, v52
	v_readfirstlane_b32 s4, v237
	s_lshl_b32 s4, s4, 5
	s_add_i32 s4, s4, s28
	s_mov_b32 s12, 0
	s_mov_b32 s13, s12
	s_mov_b32 s14, s12
	s_mov_b32 s15, s12
	s_mov_b32 s16, s12
	s_mov_b32 s17, s12
	s_mov_b32 s18, s12
	s_mov_b32 s19, s12
	s_mov_b32 s20, s12
	s_mov_b32 s21, s12
	s_mov_b32 s22, s12
	s_mov_b32 s23, s12
	s_mov_b32 s24, s12
	s_mov_b32 s25, s12
	s_mov_b32 s26, s12
	s_mov_b32 s27, s12
	v_add_u32_e32 v245, s6, v50
	v_lshl_add_u64 v[224:225], s[80:81], 0, v[48:49]
	v_lshl_add_u64 v[226:227], s[78:79], 0, v[48:49]
	s_mov_b32 s31, 2
	v_lshlrev_b32_e32 v242, 2, v236
	v_lshl_add_u32 v243, v238, 2, v239
	v_mov_b32_e32 v246, 0
	s_waitcnt vmcnt(0)
	ds_write_b128 v247, v[2:5]
	ds_write_b128 v248, v[6:9]
	ds_write_b128 v250, v[10:13] offset:32768
	ds_write_b128 v251, v[14:17] offset:32768
	s_waitcnt lgkmcnt(0)
	s_barrier
	ds_read_b128 v[16:19], v249 offset:32768
	ds_read_b128 v[20:23], v249 offset:40960
	s_waitcnt lgkmcnt(1)
	v_mfma_f32_32x32x16_bf16 v[32:47], v[16:19], v[174:177], 0
	ds_read_b128 v[52:55], v252 offset:32768
	ds_read_b128 v[56:59], v252 offset:40960
	v_mov_b64_e32 v[0:1], s[12:13]
	v_mov_b64_e32 v[2:3], s[14:15]
	v_mov_b64_e32 v[4:5], s[16:17]
	v_mov_b64_e32 v[6:7], s[18:19]
	v_mov_b64_e32 v[8:9], s[20:21]
	v_mov_b64_e32 v[10:11], s[22:23]
	s_waitcnt lgkmcnt(2)
	v_mfma_f32_32x32x16_bf16 v[16:31], v[20:23], v[174:177], 0
	v_mov_b64_e32 v[12:13], s[24:25]
	v_mov_b64_e32 v[14:15], s[26:27]
	v_mov_b64_e32 v[94:95], v[14:15]
	v_mov_b64_e32 v[78:79], v[14:15]
	s_mov_b64 s[16:17], 0
	v_mov_b64_e32 v[92:93], v[12:13]
	v_mov_b64_e32 v[90:91], v[10:11]
	s_waitcnt lgkmcnt(1)
	v_mfma_f32_32x32x16_bf16 v[32:47], v[52:55], v[170:173], v[32:47]
	v_or_b32_e32 v52, 64, v144
	v_bitop3_b32 v52, v52, v51, v60 bitop3:0xde
	v_add_u32_e32 v232, 0, v52
	v_mov_b64_e32 v[88:89], v[8:9]
	v_mov_b64_e32 v[86:87], v[6:7]
	v_mov_b64_e32 v[84:85], v[4:5]
	v_mov_b64_e32 v[82:83], v[2:3]
	s_waitcnt lgkmcnt(0)
	v_mfma_f32_32x32x16_bf16 v[16:31], v[56:59], v[170:173], v[16:31]
	ds_read_b128 v[52:55], v232 offset:32768
	ds_read_b128 v[56:59], v232 offset:40960
	v_mov_b64_e32 v[80:81], v[0:1]
	v_mov_b64_e32 v[76:77], v[12:13]
	v_mov_b64_e32 v[74:75], v[10:11]
	v_mov_b64_e32 v[72:73], v[8:9]
	v_mov_b64_e32 v[70:71], v[6:7]
	v_mov_b64_e32 v[68:69], v[4:5]
	s_waitcnt lgkmcnt(1)
	v_mfma_f32_32x32x16_bf16 v[32:47], v[52:55], v[166:169], v[32:47]
	v_or_b32_e32 v52, 0x60, v144
	v_bitop3_b32 v52, v52, v51, v60 bitop3:0xde
	v_add_u32_e32 v216, 0, v52
	v_mov_b64_e32 v[66:67], v[2:3]
	v_mov_b64_e32 v[64:65], v[0:1]
	s_waitcnt lgkmcnt(0)
	v_mfma_f32_32x32x16_bf16 v[16:31], v[56:59], v[166:169], v[16:31]
	ds_read_b128 v[52:55], v216 offset:32768
	ds_read_b128 v[56:59], v216 offset:40960
	s_waitcnt lgkmcnt(1)
	v_mfma_f32_32x32x16_bf16 v[32:47], v[52:55], v[162:165], v[32:47]
	v_or_b32_e32 v52, 0x80, v144
	v_bitop3_b32 v52, v52, v51, v60 bitop3:0xde
	v_add_u32_e32 v217, 0, v52
	s_waitcnt lgkmcnt(0)
	v_mfma_f32_32x32x16_bf16 v[16:31], v[56:59], v[162:165], v[16:31]
	ds_read_b128 v[52:55], v217 offset:32768
	ds_read_b128 v[56:59], v217 offset:40960
	s_waitcnt lgkmcnt(1)
	v_mfma_f32_32x32x16_bf16 v[32:47], v[52:55], v[158:161], v[32:47]
	v_or_b32_e32 v52, 0xa0, v144
	v_bitop3_b32 v52, v52, v51, v60 bitop3:0xde
	v_add_u32_e32 v218, 0, v52
	s_waitcnt lgkmcnt(0)
	v_mfma_f32_32x32x16_bf16 v[16:31], v[56:59], v[158:161], v[16:31]
	ds_read_b128 v[52:55], v218 offset:32768
	ds_read_b128 v[56:59], v218 offset:40960
	s_waitcnt lgkmcnt(1)
	v_mfma_f32_32x32x16_bf16 v[32:47], v[52:55], v[154:157], v[32:47]
	v_or_b32_e32 v52, 0xc0, v144
	v_bitop3_b32 v52, v52, v51, v60 bitop3:0xde
	v_add_u32_e32 v219, 0, v52
	s_waitcnt lgkmcnt(0)
	v_mfma_f32_32x32x16_bf16 v[16:31], v[56:59], v[154:157], v[16:31]
	ds_read_b128 v[52:55], v219 offset:32768
	ds_read_b128 v[56:59], v219 offset:40960
	s_waitcnt lgkmcnt(1)
	v_mfma_f32_32x32x16_bf16 v[32:47], v[52:55], v[150:153], v[32:47]
	v_or_b32_e32 v52, 0xe0, v144
	v_bitop3_b32 v51, v52, v51, v60 bitop3:0xde
	v_add_u32_e32 v210, 0, v51
	s_waitcnt lgkmcnt(0)
	v_mfma_f32_32x32x16_bf16 v[16:31], v[56:59], v[150:153], v[16:31]
	ds_read_b128 v[52:55], v210 offset:32768
	ds_read_b128 v[56:59], v210 offset:40960
	s_waitcnt lgkmcnt(1)
	v_mfma_f32_32x32x16_bf16 v[32:47], v[52:55], v[146:149], v[32:47]
	s_waitcnt lgkmcnt(0)
	v_mfma_f32_32x32x16_bf16 v[16:31], v[56:59], v[146:149], v[16:31]
	s_nop 9
	v_max_f32_e32 v51, v33, v33
	v_max_f32_e32 v52, v32, v32
	v_max_f32_e32 v51, v52, v51
	v_max3_f32 v51, v51, v34, v35
	v_max3_f32 v51, v51, v36, v37
	v_max3_f32 v51, v51, v38, v39
	v_max3_f32 v51, v51, v40, v41
	v_max3_f32 v51, v51, v42, v43
	v_max3_f32 v51, v51, v44, v45
	v_max3_f32 v51, v51, v46, v47
	v_max3_f32 v51, v51, v16, v17
	v_max3_f32 v51, v51, v18, v19
	v_max3_f32 v51, v51, v20, v21
	v_max3_f32 v51, v51, v22, v23
	v_max3_f32 v51, v51, v24, v25
	v_max3_f32 v51, v51, v26, v27
	v_max3_f32 v51, v51, v28, v29
	v_max3_f32 v51, v51, v30, v31
	v_mov_b32_e32 v52, v51
	s_nop 1
	v_permlane32_swap_b32_e32 v51, v52
	v_max_f32_e32 v52, v52, v52
	v_max_f32_e32 v51, v51, v51
	v_max_f32_e32 v51, v51, v52
	v_add_f32_e32 v52, 0x7149f2ca, v51
	v_max_f32_e32 v51, 0xf149f2ca, v51
	v_cmp_ge_f32_e32 vcc, s93, v52
	v_sub_f32_e32 v52, 0xf149f2ca, v51
	v_mul_f32_e32 v52, 0x3e0293ee, v52
	v_exp_f32_e32 v52, v52
	s_cmp_eq_u64 vcc, exec
	s_cselect_b64 vcc, -1, 0
	v_cndmask_b32_e32 v240, v51, v231, vcc
	s_add_i32 s8, s46, 0x4040
	v_cndmask_b32_e64 v128, v52, 1.0, vcc
	v_mul_f32_e32 v52, 0xbe0293ee, v240
	s_ashr_i32 s9, s8, 31
	v_fma_f32 v96, v16, s92, v52
	v_fma_f32 v97, v17, s92, v52
	v_lshl_add_u64 v[16:17], v[220:221], 0, s[8:9]
	v_fma_f32 v100, v20, s92, v52
	v_fma_f32 v101, v21, s92, v52
	v_fma_f32 v98, v18, s92, v52
	v_fma_f32 v99, v19, s92, v52
	v_mul_lo_u32 v18, v17, s40
	v_mul_lo_u32 v19, v16, s41
	v_mad_u64_u32 v[16:17], s[14:15], v16, s40, 0
	v_lshl_add_u64 v[20:21], v[222:223], 0, s[8:9]
	v_fma_f32 v102, v22, s92, v52
	v_fma_f32 v103, v23, s92, v52
	v_add3_u32 v17, v17, v19, v18
	v_mul_lo_u32 v22, v21, s40
	v_mul_lo_u32 v23, v20, s41
	v_mad_u64_u32 v[20:21], s[8:9], v20, s40, 0
	v_fma_f32 v104, v24, s92, v52
	v_fma_f32 v105, v25, s92, v52
	v_lshlrev_b64 v[24:25], 1, v[16:17]
	v_add3_u32 v21, v21, v23, v22
	v_fma_f32 v108, v28, s92, v52
	v_fma_f32 v109, v29, s92, v52
	v_lshl_add_u64 v[16:17], s[80:81], 0, v[24:25]
	v_lshlrev_b64 v[28:29], 1, v[20:21]
	v_lshl_add_u64 v[16:17], v[16:17], 0, v[48:49]
	v_lshl_add_u64 v[20:21], s[80:81], 0, v[28:29]
	global_load_dwordx4 v[16:19], v[16:17], off
	v_lshl_add_u64 v[20:21], v[20:21], 0, v[48:49]
	v_lshl_add_u64 v[24:25], s[78:79], 0, v[24:25]
	global_load_dwordx4 v[20:23], v[20:21], off
	v_lshl_add_u64 v[24:25], v[24:25], 0, v[48:49]
	v_lshl_add_u64 v[28:29], s[78:79], 0, v[28:29]
	v_fma_f32 v106, v26, s92, v52
	v_fma_f32 v107, v27, s92, v52
	global_load_dwordx4 v[24:27], v[24:25], off
	v_lshl_add_u64 v[28:29], v[28:29], 0, v[48:49]
	v_fma_f32 v110, v30, s92, v52
	v_fma_f32 v111, v31, s92, v52
	global_load_dwordx4 v[28:31], v[28:29], off
	v_mov_b32_e32 v51, v52
	v_fmamk_f32 v32, v32, 0x3e0293ee, v52
	v_fmamk_f32 v33, v33, 0x3e0293ee, v52
	v_fmamk_f32 v34, v34, 0x3e0293ee, v52
	v_fmamk_f32 v35, v35, 0x3e0293ee, v52
	v_fmamk_f32 v36, v36, 0x3e0293ee, v52
	v_fmamk_f32 v37, v37, 0x3e0293ee, v52
	v_fmamk_f32 v38, v38, 0x3e0293ee, v52
	v_fmamk_f32 v39, v39, 0x3e0293ee, v52
	v_fmamk_f32 v40, v40, 0x3e0293ee, v52
	v_fmamk_f32 v41, v41, 0x3e0293ee, v52
	v_fmamk_f32 v42, v42, 0x3e0293ee, v52
	v_fmamk_f32 v43, v43, 0x3e0293ee, v52
	v_fmamk_f32 v44, v44, 0x3e0293ee, v52
	v_fmamk_f32 v45, v45, 0x3e0293ee, v52
	v_fmamk_f32 v46, v46, 0x3e0293ee, v52
	v_fmac_f32_e32 v51, 0x3e0293ee, v47
	s_ashr_i32 s4, s4, 6
	v_exp_f32_e32 v112, v32
	v_exp_f32_e32 v113, v33
	v_exp_f32_e32 v114, v34
	v_exp_f32_e32 v115, v35
	v_exp_f32_e32 v116, v36
	v_exp_f32_e32 v117, v37
	v_exp_f32_e32 v118, v38
	v_exp_f32_e32 v119, v39
	v_exp_f32_e32 v120, v40
	v_exp_f32_e32 v121, v41
	v_exp_f32_e32 v122, v42
	v_exp_f32_e32 v123, v43
	v_exp_f32_e32 v124, v44
	v_exp_f32_e32 v125, v45
	v_exp_f32_e32 v126, v46
	v_exp_f32_e32 v127, v51
	s_max_i32 s4, s4, 4
	s_waitcnt vmcnt(0)
	s_add_i32 s4, s4, -4
	s_addk_i32 s6, 0x4000
	s_waitcnt vmcnt(3)
	ds_write_b128 v247, v[16:19] offset:16384
	s_waitcnt vmcnt(2)
	ds_write_b128 v248, v[20:23] offset:16384
	s_waitcnt vmcnt(1)
	ds_write_b128 v250, v[24:27] offset:49152
	s_waitcnt vmcnt(0)
	ds_write_b128 v251, v[28:31] offset:49152
	s_min_u32 s20, s4, 56
	v_add_u32_e32 v244, s6, v50
	v_mov_b64_e32 v[62:63], v[14:15]
	v_mov_b64_e32 v[46:47], v[14:15]
	v_mov_b64_e32 v[30:31], v[14:15]
	s_add_i32 s13, s20, 8
	v_cmp_gt_u32_e64 s[4:5], 32, v233
	s_lshr_b32 s21, s49, 6
	s_add_i32 s22, s46, 0x4080
	s_add_i32 s23, s68, 0xffffff80
	v_mov_b64_e32 v[60:61], v[12:13]
	v_mov_b64_e32 v[58:59], v[10:11]
	v_mov_b64_e32 v[56:57], v[8:9]
	v_mov_b64_e32 v[54:55], v[6:7]
	v_mov_b64_e32 v[52:53], v[4:5]
	v_mov_b64_e32 v[50:51], v[2:3]
	v_mov_b64_e32 v[48:49], v[0:1]
	v_mov_b64_e32 v[44:45], v[12:13]
	v_mov_b64_e32 v[42:43], v[10:11]
	v_mov_b64_e32 v[40:41], v[8:9]
	v_mov_b64_e32 v[38:39], v[6:7]
	v_mov_b64_e32 v[36:37], v[4:5]
	v_mov_b64_e32 v[34:35], v[2:3]
	v_mov_b64_e32 v[32:33], v[0:1]
	v_mov_b64_e32 v[28:29], v[12:13]
	v_mov_b64_e32 v[26:27], v[10:11]
	v_mov_b64_e32 v[24:25], v[8:9]
	v_mov_b64_e32 v[22:23], v[6:7]
	v_mov_b64_e32 v[20:21], v[4:5]
	v_mov_b64_e32 v[18:19], v[2:3]
	v_mov_b64_e32 v[16:17], v[0:1]
	s_waitcnt lgkmcnt(0)
	s_barrier
	s_branch .LBB0_535

.LBB0_576:
	v_max_f32_e32 v128, v81, v81
	v_max_f32_e32 v129, v80, v80
	v_max_f32_e32 v128, v129, v128
	v_max3_f32 v128, v128, v82, v83
	v_max3_f32 v128, v128, v84, v85
	v_max3_f32 v128, v128, v86, v87
	v_max3_f32 v128, v128, v88, v89
	v_max3_f32 v128, v128, v90, v91
	v_max3_f32 v128, v128, v92, v93
	v_max3_f32 v128, v128, v94, v95
	v_max3_f32 v128, v128, v64, v65
	v_max3_f32 v128, v128, v66, v67
	v_max3_f32 v128, v128, v68, v69
	v_max3_f32 v128, v128, v70, v71
	v_max3_f32 v128, v128, v72, v73
	v_max3_f32 v128, v128, v74, v75
	v_max3_f32 v128, v128, v76, v77
	v_max3_f32 v128, v128, v78, v79
	v_mov_b32_e32 v129, v128
	s_nop 1
	v_permlane32_swap_b32_e32 v128, v129
	v_max_f32_e32 v129, v129, v129
	v_max_f32_e32 v128, v128, v128
	v_max_f32_e32 v128, v128, v129
	v_sub_f32_e32 v129, v128, v240
	v_cmp_ge_f32_e32 vcc, s93, v129
	s_cmp_eq_u64 vcc, exec
	v_max_f32_e32 v129, v240, v240
	s_cselect_b64 vcc, -1, 0
	v_max_f32_e32 v129, v129, v128
	v_sub_f32_e32 v128, v240, v129
	v_cndmask_b32_e32 v240, v129, v240, vcc
	v_mul_f32_e32 v130, 0xbe0293ee, v240
	v_mul_f32_e32 v128, 0x3e0293ee, v128
	v_mov_b32_e32 v129, v130
	v_exp_f32_e32 v128, v128
	v_fmamk_f32 v80, v80, 0x3e0293ee, v130
	v_fmamk_f32 v81, v81, 0x3e0293ee, v130
	v_fmamk_f32 v82, v82, 0x3e0293ee, v130
	v_fmamk_f32 v83, v83, 0x3e0293ee, v130
	v_fmamk_f32 v84, v84, 0x3e0293ee, v130
	v_fmamk_f32 v85, v85, 0x3e0293ee, v130
	v_fmamk_f32 v86, v86, 0x3e0293ee, v130
	v_fmamk_f32 v87, v87, 0x3e0293ee, v130
	v_fmamk_f32 v88, v88, 0x3e0293ee, v130
	v_fmamk_f32 v89, v89, 0x3e0293ee, v130
	v_fmamk_f32 v90, v90, 0x3e0293ee, v130
	v_fmamk_f32 v91, v91, 0x3e0293ee, v130
	v_fmamk_f32 v92, v92, 0x3e0293ee, v130
	v_fmamk_f32 v93, v93, 0x3e0293ee, v130
	v_fmamk_f32 v94, v94, 0x3e0293ee, v130
	v_fmac_f32_e32 v129, 0x3e0293ee, v95
	v_exp_f32_e32 v80, v80
	v_exp_f32_e32 v81, v81
	v_exp_f32_e32 v82, v82
	v_exp_f32_e32 v83, v83
	v_exp_f32_e32 v84, v84
	v_exp_f32_e32 v85, v85
	v_exp_f32_e32 v86, v86
	v_exp_f32_e32 v87, v87
	v_exp_f32_e32 v88, v88
	v_exp_f32_e32 v89, v89
	v_exp_f32_e32 v90, v90
	v_exp_f32_e32 v91, v91
	v_exp_f32_e32 v92, v92
	v_exp_f32_e32 v93, v93
	v_exp_f32_e32 v94, v94
	v_exp_f32_e32 v95, v129
	v_cndmask_b32_e64 v128, v128, 1.0, vcc
	v_fma_f32 v78, v78, s92, v130
	v_fma_f32 v79, v79, s92, v130
	v_fma_f32 v76, v76, s92, v130
	v_fma_f32 v77, v77, s92, v130
	v_fma_f32 v74, v74, s92, v130
	v_fma_f32 v75, v75, s92, v130
	v_fma_f32 v72, v72, s92, v130
	v_fma_f32 v73, v73, s92, v130
	v_fma_f32 v70, v70, s92, v130
	v_fma_f32 v71, v71, s92, v130
	v_fma_f32 v68, v68, s92, v130
	v_fma_f32 v69, v69, s92, v130
	v_fma_f32 v66, v66, s92, v130
	v_fma_f32 v67, v67, s92, v130
	v_fma_f32 v64, v64, s92, v130
	v_fma_f32 v65, v65, s92, v130

.LBB0_622:
	v_max_f32_e32 v128, v113, v113
	v_max_f32_e32 v129, v112, v112
	v_max_f32_e32 v128, v129, v128
	v_max3_f32 v128, v128, v114, v115
	v_max3_f32 v128, v128, v116, v117
	v_max3_f32 v128, v128, v118, v119
	v_max3_f32 v128, v128, v120, v121
	v_max3_f32 v128, v128, v122, v123
	v_max3_f32 v128, v128, v124, v125
	v_max3_f32 v128, v128, v126, v127
	v_max3_f32 v128, v128, v96, v97
	v_max3_f32 v128, v128, v98, v99
	v_max3_f32 v128, v128, v100, v101
	v_max3_f32 v128, v128, v102, v103
	v_max3_f32 v128, v128, v104, v105
	v_max3_f32 v128, v128, v106, v107
	v_max3_f32 v128, v128, v108, v109
	v_max3_f32 v128, v128, v110, v111
	v_mov_b32_e32 v129, v128
	s_nop 1
	v_permlane32_swap_b32_e32 v128, v129
	v_max_f32_e32 v129, v129, v129
	v_max_f32_e32 v128, v128, v128
	v_max_f32_e32 v128, v128, v129
	v_sub_f32_e32 v129, v128, v240
	v_cmp_ge_f32_e32 vcc, s93, v129
	s_cmp_eq_u64 vcc, exec
	v_max_f32_e32 v129, v240, v240
	s_cselect_b64 vcc, -1, 0
	v_max_f32_e32 v129, v129, v128
	v_sub_f32_e32 v128, v240, v129
	v_cndmask_b32_e32 v240, v129, v240, vcc
	v_mul_f32_e32 v130, 0xbe0293ee, v240
	v_mul_f32_e32 v128, 0x3e0293ee, v128
	v_mov_b32_e32 v129, v130
	v_exp_f32_e32 v128, v128
	v_fmamk_f32 v112, v112, 0x3e0293ee, v130
	v_fmamk_f32 v113, v113, 0x3e0293ee, v130
	v_fmamk_f32 v114, v114, 0x3e0293ee, v130
	v_fmamk_f32 v115, v115, 0x3e0293ee, v130
	v_fmamk_f32 v116, v116, 0x3e0293ee, v130
	v_fmamk_f32 v117, v117, 0x3e0293ee, v130
	v_fmamk_f32 v118, v118, 0x3e0293ee, v130
	v_fmamk_f32 v119, v119, 0x3e0293ee, v130
	v_fmamk_f32 v120, v120, 0x3e0293ee, v130
	v_fmamk_f32 v121, v121, 0x3e0293ee, v130
	v_fmamk_f32 v122, v122, 0x3e0293ee, v130
	v_fmamk_f32 v123, v123, 0x3e0293ee, v130
	v_fmamk_f32 v124, v124, 0x3e0293ee, v130
	v_fmamk_f32 v125, v125, 0x3e0293ee, v130
	v_fmamk_f32 v126, v126, 0x3e0293ee, v130
	v_fmac_f32_e32 v129, 0x3e0293ee, v127
	v_exp_f32_e32 v112, v112
	v_exp_f32_e32 v113, v113
	v_exp_f32_e32 v114, v114
	v_exp_f32_e32 v115, v115
	v_exp_f32_e32 v116, v116
	v_exp_f32_e32 v117, v117
	v_exp_f32_e32 v118, v118
	v_exp_f32_e32 v119, v119
	v_exp_f32_e32 v120, v120
	v_exp_f32_e32 v121, v121
	v_exp_f32_e32 v122, v122
	v_exp_f32_e32 v123, v123
	v_exp_f32_e32 v124, v124
	v_exp_f32_e32 v125, v125
	v_exp_f32_e32 v126, v126
	v_exp_f32_e32 v127, v129
	v_cndmask_b32_e64 v128, v128, 1.0, vcc
	v_fma_f32 v110, v110, s92, v130
	v_fma_f32 v111, v111, s92, v130
	v_fma_f32 v108, v108, s92, v130
	v_fma_f32 v109, v109, s92, v130
	v_fma_f32 v106, v106, s92, v130
	v_fma_f32 v107, v107, s92, v130
	v_fma_f32 v104, v104, s92, v130
	v_fma_f32 v105, v105, s92, v130
	v_fma_f32 v102, v102, s92, v130
	v_fma_f32 v103, v103, s92, v130
	v_fma_f32 v100, v100, s92, v130
	v_fma_f32 v101, v101, s92, v130
	v_fma_f32 v98, v98, s92, v130
	v_fma_f32 v99, v99, s92, v130
	v_fma_f32 v96, v96, s92, v130
	v_fma_f32 v97, v97, s92, v130

.LBB0_667:
	v_max_f32_e32 v96, v81, v81
	v_max_f32_e32 v97, v80, v80
	v_max_f32_e32 v96, v97, v96
	v_max3_f32 v96, v96, v82, v83
	v_max3_f32 v96, v96, v84, v85
	v_max3_f32 v96, v96, v86, v87
	v_max3_f32 v96, v96, v88, v89
	v_max3_f32 v96, v96, v90, v91
	v_max3_f32 v96, v96, v92, v93
	v_max3_f32 v96, v96, v94, v95
	v_max3_f32 v96, v96, v64, v65
	v_max3_f32 v96, v96, v66, v67
	v_max3_f32 v96, v96, v68, v69
	v_max3_f32 v96, v96, v70, v71
	v_max3_f32 v96, v96, v72, v73
	v_max3_f32 v96, v96, v74, v75
	v_max3_f32 v96, v96, v76, v77
	v_max3_f32 v96, v96, v78, v79
	v_mov_b32_e32 v97, v96
	s_nop 1
	v_permlane32_swap_b32_e32 v96, v97
	v_max_f32_e32 v97, v97, v97
	v_max_f32_e32 v96, v96, v96
	v_max_f32_e32 v96, v96, v97
	v_sub_f32_e32 v97, v96, v240
	v_cmp_ge_f32_e32 vcc, s93, v97
	s_cmp_eq_u64 vcc, exec
	v_max_f32_e32 v97, v240, v240
	s_cselect_b64 vcc, -1, 0
	v_max_f32_e32 v97, v97, v96
	v_sub_f32_e32 v96, v240, v97
	v_cndmask_b32_e32 v240, v97, v240, vcc
	v_mul_f32_e32 v98, 0xbe0293ee, v240
	v_mul_f32_e32 v96, 0x3e0293ee, v96
	v_mov_b32_e32 v97, v98
	v_exp_f32_e32 v96, v96
	v_fmamk_f32 v80, v80, 0x3e0293ee, v98
	v_fmamk_f32 v81, v81, 0x3e0293ee, v98
	v_fmamk_f32 v82, v82, 0x3e0293ee, v98
	v_fmamk_f32 v83, v83, 0x3e0293ee, v98
	v_fmamk_f32 v84, v84, 0x3e0293ee, v98
	v_fmamk_f32 v85, v85, 0x3e0293ee, v98
	v_fmamk_f32 v86, v86, 0x3e0293ee, v98
	v_fmamk_f32 v87, v87, 0x3e0293ee, v98
	v_fmamk_f32 v88, v88, 0x3e0293ee, v98
	v_fmamk_f32 v89, v89, 0x3e0293ee, v98
	v_fmamk_f32 v90, v90, 0x3e0293ee, v98
	v_fmamk_f32 v91, v91, 0x3e0293ee, v98
	v_fmamk_f32 v92, v92, 0x3e0293ee, v98
	v_fmamk_f32 v93, v93, 0x3e0293ee, v98
	v_fmamk_f32 v94, v94, 0x3e0293ee, v98
	v_fmac_f32_e32 v97, 0x3e0293ee, v95
	v_exp_f32_e32 v80, v80
	v_exp_f32_e32 v81, v81
	v_exp_f32_e32 v82, v82
	v_exp_f32_e32 v83, v83
	v_exp_f32_e32 v84, v84
	v_exp_f32_e32 v85, v85
	v_exp_f32_e32 v86, v86
	v_exp_f32_e32 v87, v87
	v_exp_f32_e32 v88, v88
	v_exp_f32_e32 v89, v89
	v_exp_f32_e32 v90, v90
	v_exp_f32_e32 v91, v91
	v_exp_f32_e32 v92, v92
	v_exp_f32_e32 v93, v93
	v_exp_f32_e32 v94, v94
	v_exp_f32_e32 v95, v97
	v_cndmask_b32_e64 v96, v96, 1.0, vcc
	v_fma_f32 v78, v78, s92, v98
	v_fma_f32 v79, v79, s92, v98
	v_fma_f32 v76, v76, s92, v98
	v_fma_f32 v77, v77, s92, v98
	v_fma_f32 v74, v74, s92, v98
	v_fma_f32 v75, v75, s92, v98
	v_fma_f32 v72, v72, s92, v98
	v_fma_f32 v73, v73, s92, v98
	v_fma_f32 v70, v70, s92, v98
	v_fma_f32 v71, v71, s92, v98
	v_fma_f32 v68, v68, s92, v98
	v_fma_f32 v69, v69, s92, v98
	v_fma_f32 v66, v66, s92, v98
	v_fma_f32 v67, v67, s92, v98
	v_fma_f32 v64, v64, s92, v98
	v_fma_f32 v65, v65, s92, v98

.LBB0_677:
	s_and_b64 vcc, exec, s[4:5]
	s_cbranch_vccz .LBB0_760
	s_cmp_lg_u32 s29, 1
	s_cselect_b64 s[4:5], -1, 0
	s_or_b64 s[6:7], s[10:11], s[4:5]
	s_mov_b64 s[4:5], -1
	s_and_b64 vcc, exec, s[6:7]
	s_cbranch_vccnz .LBB0_737
	v_mbcnt_lo_u32_b32 v0, -1, 0
	v_mbcnt_hi_u32_b32 v0, -1, v0
	s_add_i32 s4, 0, 0x10000
	v_add_u32_e32 v16, s66, v0
	s_cmp_lg_u32 0, -1
	v_ashrrev_i32_e32 v206, 6, v16
	v_and_b32_e32 v207, 31, v16
	v_lshlrev_b32_e32 v203, 5, v206
	v_and_b32_e32 v0, 0x3fffffc0, v16
	v_or_b32_e32 v2, v203, v207
	v_lshl_add_u32 v208, v0, 2, s4
	v_add_u32_e32 v0, s30, v2
	v_ashrrev_i32_e32 v1, 31, v0
	v_mul_lo_u32 v3, s40, v1
	v_mul_lo_u32 v4, s41, v0
	v_mad_u64_u32 v[0:1], s[4:5], s40, v0, 0
	v_bfe_u32 v205, v16, 5, 1
	v_add3_u32 v1, v1, v3, v4
	v_lshl_add_u64 v[0:1], v[0:1], 1, s[88:89]
	v_lshlrev_b32_e32 v144, 4, v205
	v_ashrrev_i32_e32 v194, 4, v16
	v_lshl_add_u64 v[0:1], v[0:1], 0, v[144:145]
	v_add_u32_e32 v220, s28, v2
	v_and_b32_e32 v2, 0xfffff0, v194
	v_lshlrev_b32_e32 v3, 1, v194
	global_load_dwordx4 v[158:161], v[0:1], off
	global_load_dwordx4 v[154:157], v[0:1], off offset:32
	global_load_dwordx4 v[150:153], v[0:1], off offset:64
	global_load_dwordx4 v[146:149], v[0:1], off offset:96
	global_load_dwordx4 v[140:143], v[0:1], off offset:128
	global_load_dwordx4 v[136:139], v[0:1], off offset:160
	global_load_dwordx4 v[132:135], v[0:1], off offset:192
	global_load_dwordx4 v[128:131], v[0:1], off offset:224
	v_lshlrev_b32_e32 v0, 3, v16
	v_and_or_b32 v2, v3, 8, v2
	v_and_b32_e32 v1, 0x78, v0
	v_lshrrev_b32_e32 v3, 1, v194
	v_lshrrev_b32_e32 v2, 1, v2
	v_bfe_u32 v0, v0, 5, 2
	v_and_b32_e32 v4, 3, v194
	v_or_b32_e32 v2, v2, v0
	v_and_or_b32 v3, v3, 4, v4
	v_lshlrev_b32_e32 v48, 1, v1
	v_lshlrev_b32_e32 v2, 9, v2
	v_lshlrev_b32_e32 v3, 6, v3
	v_and_b32_e32 v1, 48, v48
	v_add_u32_e32 v18, 32, v194
	v_or3_b32 v17, v2, v3, v1
	v_and_b32_e32 v2, 0xfffff0, v18
	v_lshlrev_b32_e32 v4, 1, v18
	v_and_or_b32 v2, v4, 8, v2
	v_lshrrev_b32_e32 v2, 1, v2
	v_or_b32_e32 v0, v2, v0
	v_and_b32_e32 v202, 63, v16
	v_lshlrev_b32_e32 v0, 9, v0
	v_lshlrev_b32_e32 v204, 4, v16
	v_or3_b32 v19, v0, v3, v1
	v_lshlrev_b32_e32 v0, 3, v202
	v_and_b32_e32 v1, 0xc0, v204
	v_lshlrev_b32_e32 v2, 1, v16
	v_and_or_b32 v1, v0, 24, v1
	v_and_b32_e32 v2, 32, v2
	v_and_b32_e32 v0, 0x100, v0
	s_cselect_b32 s6, 0, 0
	s_ashr_i32 s83, s82, 31
	v_ashrrev_i32_e32 v195, 31, v194
	v_or3_b32 v50, v1, v2, v0
	v_lshl_add_u64 v[0:1], v[194:195], 0, s[82:83]
	v_mul_lo_u32 v2, v1, s40
	v_mul_lo_u32 v3, v0, s41
	v_mad_u64_u32 v[0:1], s[8:9], v0, s40, 0
	v_add3_u32 v1, v1, v3, v2
	v_lshlrev_b64 v[8:9], 1, v[0:1]
	v_lshl_add_u64 v[0:1], s[80:81], 0, v[8:9]
	v_mov_b32_e32 v49, v145
	v_lshl_add_u64 v[0:1], v[0:1], 0, v[48:49]
	v_lshl_add_u64 v[196:197], v[194:195], 0, 32
	global_load_dwordx4 v[0:3], v[0:1], off
	v_lshl_add_u64 v[4:5], v[196:197], 0, s[82:83]
	v_mul_lo_u32 v6, v5, s40
	v_mul_lo_u32 v7, v4, s41
	v_mad_u64_u32 v[4:5], s[8:9], v4, s40, 0
	v_add3_u32 v5, v5, v7, v6
	v_lshlrev_b64 v[12:13], 1, v[4:5]
	v_lshl_add_u64 v[4:5], s[80:81], 0, v[12:13]
	v_lshl_add_u64 v[8:9], s[78:79], 0, v[8:9]
	v_lshl_add_u64 v[12:13], s[78:79], 0, v[12:13]
	v_lshl_add_u64 v[4:5], v[4:5], 0, v[48:49]
	v_lshl_add_u64 v[8:9], v[8:9], 0, v[48:49]
	v_lshl_add_u64 v[12:13], v[12:13], 0, v[48:49]
	global_load_dwordx4 v[4:7], v[4:5], off
	v_add_u32_e32 v218, 0, v17
	global_load_dwordx4 v[8:11], v[8:9], off
	v_lshlrev_b32_e32 v51, 8, v207
	global_load_dwordx4 v[12:15], v[12:13], off
	s_waitcnt vmcnt(0)
	v_and_b32_e32 v60, 0x70, v204
	v_add_u32_e32 v219, 0, v19
	v_or_b32_e32 v52, 32, v144
	v_bitop3_b32 v52, v52, v51, v60 bitop3:0xde
	v_add_u32_e32 v225, 0, v52
	v_readfirstlane_b32 s4, v206
	s_lshl_b32 s4, s4, 5
	s_add_i32 s4, s4, s28
	s_mov_b32 s52, 0
	s_mov_b32 s53, s52
	s_mov_b64 s[44:45], s[54:55]
	s_mov_b32 s54, s52
	s_mov_b32 s55, s52
	s_mov_b32 s56, s52
	s_mov_b32 s57, s52
	s_mov_b32 s58, s52
	s_mov_b32 s59, s52
	s_mov_b32 s60, s52
	s_mov_b32 s61, s52
	s_mov_b32 s62, s52
	s_mov_b32 s63, s52
	s_mov_b32 s64, s52
	s_mov_b32 s65, s52
	s_mov_b32 s66, s52
	s_mov_b32 s67, s52
	v_lshlrev_b32_e32 v210, 2, v205
	v_add_u32_e32 v216, s6, v50
	v_lshl_add_u64 v[198:199], s[80:81], 0, v[48:49]
	v_lshl_add_u64 v[200:201], s[78:79], 0, v[48:49]
	s_mov_b32 s95, 2
	v_lshl_add_u32 v211, v207, 2, v208
	v_mov_b32_e32 v221, 0
	s_waitcnt vmcnt(0)
	ds_write_b128 v218, v[0:3]
	v_lshlrev_b32_e32 v0, 8, v194
	v_and_b32_e32 v1, 0x70, v16
	v_bitop3_b32 v0, v48, v0, v1 bitop3:0xde
	v_add_u32_e32 v223, 0, v0
	v_lshlrev_b32_e32 v0, 8, v18
	v_bitop3_b32 v0, v48, v0, v1 bitop3:0xde
	v_add_u32_e32 v224, 0, v0
	v_bitop3_b32 v0, v144, v51, v60 bitop3:0xde
	v_add_u32_e32 v222, 0, v0
	ds_write_b128 v219, v[4:7]
	ds_write_b128 v223, v[8:11] offset:32768
	ds_write_b128 v224, v[12:15] offset:32768
	s_waitcnt lgkmcnt(0)
	s_barrier
	ds_read_b128 v[16:19], v222 offset:32768
	ds_read_b128 v[20:23], v222 offset:40960
	s_waitcnt lgkmcnt(1)
	v_mfma_f32_32x32x16_bf16 v[32:47], v[16:19], v[158:161], 0
	ds_read_b128 v[52:55], v225 offset:32768
	ds_read_b128 v[56:59], v225 offset:40960
	v_mov_b64_e32 v[0:1], s[52:53]
	v_mov_b64_e32 v[14:15], s[66:67]
	v_mov_b64_e32 v[2:3], s[54:55]
	v_mov_b64_e32 v[4:5], s[56:57]
	v_mov_b64_e32 v[6:7], s[58:59]
	v_mov_b64_e32 v[8:9], s[60:61]
	s_waitcnt lgkmcnt(2)
	v_mfma_f32_32x32x16_bf16 v[16:31], v[20:23], v[158:161], 0
	v_mov_b64_e32 v[10:11], s[62:63]
	v_mov_b64_e32 v[12:13], s[64:65]
	v_mov_b64_e32 v[94:95], v[14:15]
	v_mov_b64_e32 v[78:79], v[14:15]
	v_readlane_b32 s61, v255, 2
	v_readlane_b32 s66, v253, 1
	s_mov_b64 s[54:55], 0
	s_waitcnt lgkmcnt(1)
	v_mfma_f32_32x32x16_bf16 v[32:47], v[52:55], v[154:157], v[32:47]
	v_or_b32_e32 v52, 64, v144
	v_bitop3_b32 v52, v52, v51, v60 bitop3:0xde
	v_add_u32_e32 v226, 0, v52
	v_mov_b64_e32 v[92:93], v[12:13]
	v_mov_b64_e32 v[90:91], v[10:11]
	v_mov_b64_e32 v[88:89], v[8:9]
	v_mov_b64_e32 v[86:87], v[6:7]
	s_waitcnt lgkmcnt(0)
	v_mfma_f32_32x32x16_bf16 v[16:31], v[56:59], v[154:157], v[16:31]
	ds_read_b128 v[52:55], v226 offset:32768
	ds_read_b128 v[56:59], v226 offset:40960
	v_mov_b64_e32 v[84:85], v[4:5]
	v_mov_b64_e32 v[82:83], v[2:3]
	v_mov_b64_e32 v[80:81], v[0:1]
	v_mov_b64_e32 v[76:77], v[12:13]
	v_mov_b64_e32 v[74:75], v[10:11]
	v_mov_b64_e32 v[72:73], v[8:9]
	s_waitcnt lgkmcnt(1)
	v_mfma_f32_32x32x16_bf16 v[32:47], v[52:55], v[150:153], v[32:47]
	v_or_b32_e32 v52, 0x60, v144
	v_bitop3_b32 v52, v52, v51, v60 bitop3:0xde
	v_add_u32_e32 v227, 0, v52
	v_mov_b64_e32 v[70:71], v[6:7]
	v_mov_b64_e32 v[68:69], v[4:5]
	v_mov_b64_e32 v[66:67], v[2:3]
	v_mov_b64_e32 v[64:65], v[0:1]
	s_waitcnt lgkmcnt(0)
	v_mfma_f32_32x32x16_bf16 v[16:31], v[56:59], v[150:153], v[16:31]
	ds_read_b128 v[52:55], v227 offset:32768
	ds_read_b128 v[56:59], v227 offset:40960
	s_mov_b32 s62, 0xf149f2ca
	s_movk_i32 s63, 0xfeff
	s_waitcnt lgkmcnt(1)
	v_mfma_f32_32x32x16_bf16 v[32:47], v[52:55], v[146:149], v[32:47]
	v_or_b32_e32 v52, 0x80, v144
	v_bitop3_b32 v52, v52, v51, v60 bitop3:0xde
	v_add_u32_e32 v232, 0, v52
	s_waitcnt lgkmcnt(0)
	v_mfma_f32_32x32x16_bf16 v[16:31], v[56:59], v[146:149], v[16:31]
	ds_read_b128 v[52:55], v232 offset:32768
	ds_read_b128 v[56:59], v232 offset:40960
	s_waitcnt lgkmcnt(1)
	v_mfma_f32_32x32x16_bf16 v[32:47], v[52:55], v[140:143], v[32:47]
	v_or_b32_e32 v52, 0xa0, v144
	v_bitop3_b32 v52, v52, v51, v60 bitop3:0xde
	v_add_u32_e32 v233, 0, v52
	s_waitcnt lgkmcnt(0)
	v_mfma_f32_32x32x16_bf16 v[16:31], v[56:59], v[140:143], v[16:31]
	ds_read_b128 v[52:55], v233 offset:32768
	ds_read_b128 v[56:59], v233 offset:40960
	s_waitcnt lgkmcnt(1)
	v_mfma_f32_32x32x16_bf16 v[32:47], v[52:55], v[136:139], v[32:47]
	v_or_b32_e32 v52, 0xc0, v144
	v_bitop3_b32 v52, v52, v51, v60 bitop3:0xde
	v_add_u32_e32 v234, 0, v52
	s_waitcnt lgkmcnt(0)
	v_mfma_f32_32x32x16_bf16 v[16:31], v[56:59], v[136:139], v[16:31]
	ds_read_b128 v[52:55], v234 offset:32768
	ds_read_b128 v[56:59], v234 offset:40960
	s_waitcnt lgkmcnt(1)
	v_mfma_f32_32x32x16_bf16 v[32:47], v[52:55], v[132:135], v[32:47]
	v_or_b32_e32 v52, 0xe0, v144
	v_bitop3_b32 v51, v52, v51, v60 bitop3:0xde
	v_add_u32_e32 v235, 0, v51
	s_waitcnt lgkmcnt(0)
	v_mfma_f32_32x32x16_bf16 v[16:31], v[56:59], v[132:135], v[16:31]
	ds_read_b128 v[52:55], v235 offset:32768
	ds_read_b128 v[56:59], v235 offset:40960
	s_waitcnt lgkmcnt(1)
	v_mfma_f32_32x32x16_bf16 v[32:47], v[52:55], v[128:131], v[32:47]
	s_waitcnt lgkmcnt(0)
	v_mfma_f32_32x32x16_bf16 v[16:31], v[56:59], v[128:131], v[16:31]
	s_nop 9
	v_max_f32_e32 v51, v33, v33
	v_max_f32_e32 v52, v32, v32
	v_max_f32_e32 v51, v52, v51
	v_max3_f32 v51, v51, v34, v35
	v_max3_f32 v51, v51, v36, v37
	v_max3_f32 v51, v51, v38, v39
	v_max3_f32 v51, v51, v40, v41
	v_max3_f32 v51, v51, v42, v43
	v_max3_f32 v51, v51, v44, v45
	v_max3_f32 v51, v51, v46, v47
	v_max3_f32 v51, v51, v16, v17
	v_max3_f32 v51, v51, v18, v19
	v_max3_f32 v51, v51, v20, v21
	v_max3_f32 v51, v51, v22, v23
	v_max3_f32 v51, v51, v24, v25
	v_max3_f32 v51, v51, v26, v27
	v_max3_f32 v51, v51, v28, v29
	v_max3_f32 v51, v51, v30, v31
	v_mov_b32_e32 v52, v51
	s_nop 1
	v_permlane32_swap_b32_e32 v51, v52
	v_max_f32_e32 v52, v52, v52
	v_max_f32_e32 v51, v51, v51
	v_max_f32_e32 v51, v51, v52
	v_add_f32_e32 v52, 0x7149f2ca, v51
	v_max_f32_e32 v51, 0xf149f2ca, v51
	v_cmp_ge_f32_e32 vcc, s93, v52
	v_sub_f32_e32 v52, 0xf149f2ca, v51
	v_mul_f32_e32 v52, 0x3e0293ee, v52
	v_exp_f32_e32 v52, v52
	s_cmp_eq_u64 vcc, exec
	s_cselect_b64 vcc, -1, 0
	v_cndmask_b32_e32 v209, v51, v231, vcc
	s_add_i32 s8, s46, 0x4040
	v_cndmask_b32_e64 v237, v52, 1.0, vcc
	v_mul_f32_e32 v52, 0xbe0293ee, v209
	s_ashr_i32 s9, s8, 31
	v_fma_f32 v112, v16, s92, v52
	v_fma_f32 v113, v17, s92, v52
	v_lshl_add_u64 v[16:17], v[194:195], 0, s[8:9]
	v_fma_f32 v116, v20, s92, v52
	v_fma_f32 v117, v21, s92, v52
	v_fma_f32 v114, v18, s92, v52
	v_fma_f32 v115, v19, s92, v52
	v_mul_lo_u32 v18, v17, s40
	v_mul_lo_u32 v19, v16, s41
	v_mad_u64_u32 v[16:17], s[10:11], v16, s40, 0
	v_lshl_add_u64 v[20:21], v[196:197], 0, s[8:9]
	v_fma_f32 v118, v22, s92, v52
	v_fma_f32 v119, v23, s92, v52
	v_add3_u32 v17, v17, v19, v18
	v_mul_lo_u32 v22, v21, s40
	v_mul_lo_u32 v23, v20, s41
	v_mad_u64_u32 v[20:21], s[8:9], v20, s40, 0
	v_fma_f32 v120, v24, s92, v52
	v_fma_f32 v121, v25, s92, v52
	v_lshlrev_b64 v[24:25], 1, v[16:17]
	v_add3_u32 v21, v21, v23, v22
	v_fma_f32 v124, v28, s92, v52
	v_fma_f32 v125, v29, s92, v52
	v_lshl_add_u64 v[16:17], s[80:81], 0, v[24:25]
	v_lshlrev_b64 v[28:29], 1, v[20:21]
	v_lshl_add_u64 v[16:17], v[16:17], 0, v[48:49]
	v_lshl_add_u64 v[20:21], s[80:81], 0, v[28:29]
	global_load_dwordx4 v[16:19], v[16:17], off
	v_lshl_add_u64 v[20:21], v[20:21], 0, v[48:49]
	v_lshl_add_u64 v[24:25], s[78:79], 0, v[24:25]
	global_load_dwordx4 v[20:23], v[20:21], off
	v_lshl_add_u64 v[24:25], v[24:25], 0, v[48:49]
	v_lshl_add_u64 v[28:29], s[78:79], 0, v[28:29]
	v_fma_f32 v122, v26, s92, v52
	v_fma_f32 v123, v27, s92, v52
	global_load_dwordx4 v[24:27], v[24:25], off
	v_lshl_add_u64 v[28:29], v[28:29], 0, v[48:49]
	v_fma_f32 v126, v30, s92, v52
	v_fma_f32 v127, v31, s92, v52
	global_load_dwordx4 v[28:31], v[28:29], off
	v_mov_b32_e32 v51, v52
	v_fmamk_f32 v32, v32, 0x3e0293ee, v52
	v_fmamk_f32 v33, v33, 0x3e0293ee, v52
	v_fmamk_f32 v34, v34, 0x3e0293ee, v52
	v_fmamk_f32 v35, v35, 0x3e0293ee, v52
	v_fmamk_f32 v36, v36, 0x3e0293ee, v52
	v_fmamk_f32 v37, v37, 0x3e0293ee, v52
	v_fmamk_f32 v38, v38, 0x3e0293ee, v52
	v_fmamk_f32 v39, v39, 0x3e0293ee, v52
	v_fmamk_f32 v40, v40, 0x3e0293ee, v52
	v_fmamk_f32 v41, v41, 0x3e0293ee, v52
	v_fmamk_f32 v42, v42, 0x3e0293ee, v52
	v_fmamk_f32 v43, v43, 0x3e0293ee, v52
	v_fmamk_f32 v44, v44, 0x3e0293ee, v52
	v_fmamk_f32 v45, v45, 0x3e0293ee, v52
	v_fmamk_f32 v46, v46, 0x3e0293ee, v52
	v_fmac_f32_e32 v51, 0x3e0293ee, v47
	v_exp_f32_e32 v96, v32
	v_exp_f32_e32 v97, v33
	v_exp_f32_e32 v98, v34
	v_exp_f32_e32 v99, v35
	v_exp_f32_e32 v100, v36
	v_exp_f32_e32 v101, v37
	v_exp_f32_e32 v102, v38
	v_exp_f32_e32 v103, v39
	v_exp_f32_e32 v104, v40
	v_exp_f32_e32 v105, v41
	v_exp_f32_e32 v106, v42
	v_exp_f32_e32 v107, v43
	v_exp_f32_e32 v108, v44
	v_exp_f32_e32 v109, v45
	v_exp_f32_e32 v110, v46
	v_exp_f32_e32 v111, v51
	s_waitcnt vmcnt(0)
	s_waitcnt vmcnt(3)
	ds_write_b128 v218, v[16:19] offset:16384
	s_waitcnt vmcnt(2)
	ds_write_b128 v219, v[20:23] offset:16384
	s_waitcnt vmcnt(1)
	ds_write_b128 v223, v[24:27] offset:49152
	s_waitcnt vmcnt(0)
	ds_write_b128 v224, v[28:31] offset:49152
	s_addk_i32 s6, 0x4000
	v_add_u32_e32 v16, s49, v210
	v_add_u32_e32 v217, s6, v50
	v_sub_u32_e32 v236, v16, v220
	v_mov_b64_e32 v[62:63], v[14:15]
	v_mov_b64_e32 v[46:47], v[14:15]
	v_mov_b64_e32 v[30:31], v[14:15]
	s_add_i32 s56, s4, 0x9f
	s_add_i32 s53, s4, 0xffffff80
	v_cmp_gt_u32_e64 s[4:5], 32, v202
	s_add_i32 s57, s46, 0x4080
	s_add_i32 s58, s68, 0xffffff80
	v_mov_b64_e32 v[60:61], v[12:13]
	v_mov_b64_e32 v[58:59], v[10:11]
	v_mov_b64_e32 v[56:57], v[8:9]
	v_mov_b64_e32 v[54:55], v[6:7]
	v_mov_b64_e32 v[52:53], v[4:5]
	v_mov_b64_e32 v[50:51], v[2:3]
	v_mov_b64_e32 v[48:49], v[0:1]
	v_mov_b64_e32 v[44:45], v[12:13]
	v_mov_b64_e32 v[42:43], v[10:11]
	v_mov_b64_e32 v[40:41], v[8:9]
	v_mov_b64_e32 v[38:39], v[6:7]
	v_mov_b64_e32 v[36:37], v[4:5]
	v_mov_b64_e32 v[34:35], v[2:3]
	v_mov_b64_e32 v[32:33], v[0:1]
	v_mov_b64_e32 v[28:29], v[12:13]
	v_mov_b64_e32 v[26:27], v[10:11]
	v_mov_b64_e32 v[24:25], v[8:9]
	v_mov_b64_e32 v[22:23], v[6:7]
	v_mov_b64_e32 v[20:21], v[4:5]
	v_mov_b64_e32 v[18:19], v[2:3]
	v_mov_b64_e32 v[16:17], v[0:1]
	s_waitcnt lgkmcnt(0)
	s_barrier
	s_branch .LBB0_682

.LBB0_693:
	v_max_f32_e32 v212, v81, v81
	v_max_f32_e32 v213, v80, v80
	v_max_f32_e32 v212, v213, v212
	v_max3_f32 v212, v212, v82, v83
	v_max3_f32 v212, v212, v84, v85
	v_max3_f32 v212, v212, v86, v87
	v_max3_f32 v212, v212, v88, v89
	v_max3_f32 v212, v212, v90, v91
	v_max3_f32 v212, v212, v92, v93
	v_max3_f32 v212, v212, v94, v95
	v_max3_f32 v212, v212, v64, v65
	v_max3_f32 v212, v212, v66, v67
	v_max3_f32 v212, v212, v68, v69
	v_max3_f32 v212, v212, v70, v71
	v_max3_f32 v212, v212, v72, v73
	v_max3_f32 v212, v212, v74, v75
	v_max3_f32 v212, v212, v76, v77
	v_max3_f32 v212, v212, v78, v79
	v_mov_b32_e32 v213, v212
	s_nop 1
	v_permlane32_swap_b32_e32 v212, v213
	v_max_f32_e32 v213, v213, v213
	v_max_f32_e32 v212, v212, v212
	v_max_f32_e32 v212, v212, v213
	v_sub_f32_e32 v213, v212, v209
	v_cmp_ge_f32_e32 vcc, s93, v213
	v_max_f32_e32 v213, v209, v209
	v_max_f32_e32 v212, v213, v212
	v_sub_f32_e32 v213, v209, v212
	v_mul_f32_e32 v213, 0x3e0293ee, v213
	s_cmp_eq_u64 vcc, exec
	v_exp_f32_e32 v213, v213
	s_cselect_b64 vcc, -1, 0
	v_cndmask_b32_e32 v209, v212, v209, vcc
	v_mul_f32_e32 v212, 0xbe0293ee, v209
	v_cndmask_b32_e64 v237, v213, 1.0, vcc
	v_mov_b32_e32 v213, v212
	v_fmamk_f32 v80, v80, 0x3e0293ee, v212
	v_fmamk_f32 v81, v81, 0x3e0293ee, v212
	v_fmamk_f32 v82, v82, 0x3e0293ee, v212
	v_fmamk_f32 v83, v83, 0x3e0293ee, v212
	v_fmamk_f32 v84, v84, 0x3e0293ee, v212
	v_fmamk_f32 v85, v85, 0x3e0293ee, v212
	v_fmamk_f32 v86, v86, 0x3e0293ee, v212
	v_fmamk_f32 v87, v87, 0x3e0293ee, v212
	v_fmamk_f32 v88, v88, 0x3e0293ee, v212
	v_fmamk_f32 v89, v89, 0x3e0293ee, v212
	v_fmamk_f32 v90, v90, 0x3e0293ee, v212
	v_fmamk_f32 v91, v91, 0x3e0293ee, v212
	v_fmamk_f32 v92, v92, 0x3e0293ee, v212
	v_fmamk_f32 v93, v93, 0x3e0293ee, v212
	v_fmamk_f32 v94, v94, 0x3e0293ee, v212
	v_fmac_f32_e32 v213, 0x3e0293ee, v95
	v_exp_f32_e32 v80, v80
	v_exp_f32_e32 v81, v81
	v_exp_f32_e32 v82, v82
	v_exp_f32_e32 v83, v83
	v_exp_f32_e32 v84, v84
	v_exp_f32_e32 v85, v85
	v_exp_f32_e32 v86, v86
	v_exp_f32_e32 v87, v87
	v_exp_f32_e32 v88, v88
	v_exp_f32_e32 v89, v89
	v_exp_f32_e32 v90, v90
	v_exp_f32_e32 v91, v91
	v_exp_f32_e32 v92, v92
	v_exp_f32_e32 v93, v93
	v_exp_f32_e32 v94, v94
	v_exp_f32_e32 v95, v213
	v_fma_f32 v78, v78, s92, v212
	v_fma_f32 v79, v79, s92, v212
	v_fma_f32 v76, v76, s92, v212
	v_fma_f32 v77, v77, s92, v212
	v_fma_f32 v74, v74, s92, v212
	v_fma_f32 v75, v75, s92, v212
	v_fma_f32 v72, v72, s92, v212
	v_fma_f32 v73, v73, s92, v212
	v_fma_f32 v70, v70, s92, v212
	v_fma_f32 v71, v71, s92, v212
	v_fma_f32 v68, v68, s92, v212
	v_fma_f32 v69, v69, s92, v212
	v_fma_f32 v66, v66, s92, v212
	v_fma_f32 v67, v67, s92, v212
	v_fma_f32 v64, v64, s92, v212
	v_fma_f32 v65, v65, s92, v212

.LBB0_709:
	v_max_f32_e32 v212, v97, v97
	v_max_f32_e32 v213, v96, v96
	v_max_f32_e32 v212, v213, v212
	v_max3_f32 v212, v212, v98, v99
	v_max3_f32 v212, v212, v100, v101
	v_max3_f32 v212, v212, v102, v103
	v_max3_f32 v212, v212, v104, v105
	v_max3_f32 v212, v212, v106, v107
	v_max3_f32 v212, v212, v108, v109
	v_max3_f32 v212, v212, v110, v111
	v_max3_f32 v212, v212, v112, v113
	v_max3_f32 v212, v212, v114, v115
	v_max3_f32 v212, v212, v116, v117
	v_max3_f32 v212, v212, v118, v119
	v_max3_f32 v212, v212, v120, v121
	v_max3_f32 v212, v212, v122, v123
	v_max3_f32 v212, v212, v124, v125
	v_max3_f32 v212, v212, v126, v127
	v_mov_b32_e32 v213, v212
	s_nop 1
	v_permlane32_swap_b32_e32 v212, v213
	v_max_f32_e32 v213, v213, v213
	v_max_f32_e32 v212, v212, v212
	v_max_f32_e32 v212, v212, v213
	v_sub_f32_e32 v213, v212, v209
	v_cmp_ge_f32_e32 vcc, s93, v213
	v_max_f32_e32 v213, v209, v209
	v_max_f32_e32 v212, v213, v212
	v_sub_f32_e32 v213, v209, v212
	v_mul_f32_e32 v213, 0x3e0293ee, v213
	s_cmp_eq_u64 vcc, exec
	v_exp_f32_e32 v213, v213
	s_cselect_b64 vcc, -1, 0
	v_cndmask_b32_e32 v209, v212, v209, vcc
	v_mul_f32_e32 v212, 0xbe0293ee, v209
	v_cndmask_b32_e64 v237, v213, 1.0, vcc
	v_mov_b32_e32 v213, v212
	v_fmamk_f32 v96, v96, 0x3e0293ee, v212
	v_fmamk_f32 v97, v97, 0x3e0293ee, v212
	v_fmamk_f32 v98, v98, 0x3e0293ee, v212
	v_fmamk_f32 v99, v99, 0x3e0293ee, v212
	v_fmamk_f32 v100, v100, 0x3e0293ee, v212
	v_fmamk_f32 v101, v101, 0x3e0293ee, v212
	v_fmamk_f32 v102, v102, 0x3e0293ee, v212
	v_fmamk_f32 v103, v103, 0x3e0293ee, v212
	v_fmamk_f32 v104, v104, 0x3e0293ee, v212
	v_fmamk_f32 v105, v105, 0x3e0293ee, v212
	v_fmamk_f32 v106, v106, 0x3e0293ee, v212
	v_fmamk_f32 v107, v107, 0x3e0293ee, v212
	v_fmamk_f32 v108, v108, 0x3e0293ee, v212
	v_fmamk_f32 v109, v109, 0x3e0293ee, v212
	v_fmamk_f32 v110, v110, 0x3e0293ee, v212
	v_fmac_f32_e32 v213, 0x3e0293ee, v111
	v_exp_f32_e32 v96, v96
	v_exp_f32_e32 v97, v97
	v_exp_f32_e32 v98, v98
	v_exp_f32_e32 v99, v99
	v_exp_f32_e32 v100, v100
	v_exp_f32_e32 v101, v101
	v_exp_f32_e32 v102, v102
	v_exp_f32_e32 v103, v103
	v_exp_f32_e32 v104, v104
	v_exp_f32_e32 v105, v105
	v_exp_f32_e32 v106, v106
	v_exp_f32_e32 v107, v107
	v_exp_f32_e32 v108, v108
	v_exp_f32_e32 v109, v109
	v_exp_f32_e32 v110, v110
	v_exp_f32_e32 v111, v213
	v_fma_f32 v126, v126, s92, v212
	v_fma_f32 v127, v127, s92, v212
	v_fma_f32 v124, v124, s92, v212
	v_fma_f32 v125, v125, s92, v212
	v_fma_f32 v122, v122, s92, v212
	v_fma_f32 v123, v123, s92, v212
	v_fma_f32 v120, v120, s92, v212
	v_fma_f32 v121, v121, s92, v212
	v_fma_f32 v118, v118, s92, v212
	v_fma_f32 v119, v119, s92, v212
	v_fma_f32 v116, v116, s92, v212
	v_fma_f32 v117, v117, s92, v212
	v_fma_f32 v114, v114, s92, v212
	v_fma_f32 v115, v115, s92, v212
	v_fma_f32 v112, v112, s92, v212
	v_fma_f32 v113, v113, s92, v212

.LBB0_727:
	v_max_f32_e32 v96, v81, v81
	v_max_f32_e32 v97, v80, v80
	v_max_f32_e32 v96, v97, v96
	v_max3_f32 v96, v96, v82, v83
	v_max3_f32 v96, v96, v84, v85
	v_max3_f32 v96, v96, v86, v87
	v_max3_f32 v96, v96, v88, v89
	v_max3_f32 v96, v96, v90, v91
	v_max3_f32 v96, v96, v92, v93
	v_max3_f32 v96, v96, v94, v95
	v_max3_f32 v96, v96, v64, v65
	v_max3_f32 v96, v96, v66, v67
	v_max3_f32 v96, v96, v68, v69
	v_max3_f32 v96, v96, v70, v71
	v_max3_f32 v96, v96, v72, v73
	v_max3_f32 v96, v96, v74, v75
	v_max3_f32 v96, v96, v76, v77
	v_max3_f32 v96, v96, v78, v79
	v_mov_b32_e32 v97, v96
	s_nop 1
	v_permlane32_swap_b32_e32 v96, v97
	v_max_f32_e32 v97, v97, v97
	v_max_f32_e32 v96, v96, v96
	v_max_f32_e32 v96, v96, v97
	v_sub_f32_e32 v97, v96, v209
	v_cmp_ge_f32_e32 vcc, s93, v97
	v_max_f32_e32 v97, v209, v209
	v_max_f32_e32 v97, v97, v96
	s_cmp_eq_u64 vcc, exec
	v_sub_f32_e32 v96, v209, v97
	s_cselect_b64 vcc, -1, 0
	v_mul_f32_e32 v96, 0x3e0293ee, v96
	v_exp_f32_e32 v96, v96
	v_cndmask_b32_e32 v209, v97, v209, vcc
	v_mul_f32_e32 v98, 0xbe0293ee, v209
	v_mov_b32_e32 v97, v98
	v_fmamk_f32 v80, v80, 0x3e0293ee, v98
	v_fmamk_f32 v81, v81, 0x3e0293ee, v98
	v_fmamk_f32 v82, v82, 0x3e0293ee, v98
	v_fmamk_f32 v83, v83, 0x3e0293ee, v98
	v_fmamk_f32 v84, v84, 0x3e0293ee, v98
	v_fmamk_f32 v85, v85, 0x3e0293ee, v98
	v_fmamk_f32 v86, v86, 0x3e0293ee, v98
	v_fmamk_f32 v87, v87, 0x3e0293ee, v98
	v_fmamk_f32 v88, v88, 0x3e0293ee, v98
	v_fmamk_f32 v89, v89, 0x3e0293ee, v98
	v_fmamk_f32 v90, v90, 0x3e0293ee, v98
	v_fmamk_f32 v91, v91, 0x3e0293ee, v98
	v_fmamk_f32 v92, v92, 0x3e0293ee, v98
	v_fmamk_f32 v93, v93, 0x3e0293ee, v98
	v_fmamk_f32 v94, v94, 0x3e0293ee, v98
	v_fmac_f32_e32 v97, 0x3e0293ee, v95
	v_cndmask_b32_e64 v96, v96, 1.0, vcc
	v_fma_f32 v78, v78, s92, v98
	v_fma_f32 v79, v79, s92, v98
	v_fma_f32 v76, v76, s92, v98
	v_fma_f32 v77, v77, s92, v98
	v_fma_f32 v74, v74, s92, v98
	v_fma_f32 v75, v75, s92, v98
	v_fma_f32 v72, v72, s92, v98
	v_fma_f32 v73, v73, s92, v98
	v_fma_f32 v70, v70, s92, v98
	v_fma_f32 v71, v71, s92, v98
	v_fma_f32 v68, v68, s92, v98
	v_fma_f32 v69, v69, s92, v98
	v_fma_f32 v66, v66, s92, v98
	v_fma_f32 v67, v67, s92, v98
	v_fma_f32 v64, v64, s92, v98
	v_fma_f32 v65, v65, s92, v98
	v_exp_f32_e32 v80, v80
	v_exp_f32_e32 v81, v81
	v_exp_f32_e32 v82, v82
	v_exp_f32_e32 v83, v83
	v_exp_f32_e32 v84, v84
	v_exp_f32_e32 v85, v85
	v_exp_f32_e32 v86, v86
	v_exp_f32_e32 v87, v87
	v_exp_f32_e32 v88, v88
	v_exp_f32_e32 v89, v89
	v_exp_f32_e32 v90, v90
	v_exp_f32_e32 v91, v91
	v_exp_f32_e32 v92, v92
	v_exp_f32_e32 v93, v93
	v_exp_f32_e32 v94, v94
	v_exp_f32_e32 v95, v97

.LBB0_737:
	s_and_b64 vcc, exec, s[4:5]
	s_cbranch_vccz .LBB0_760
	v_mbcnt_lo_u32_b32 v0, -1, 0
	v_mbcnt_hi_u32_b32 v0, -1, v0
	s_add_i32 s4, 0, 0x10000
	v_add_u32_e32 v16, s66, v0
	s_cmp_lg_u32 0, -1
	v_ashrrev_i32_e32 v190, 6, v16
	v_and_b32_e32 v191, 31, v16
	v_and_b32_e32 v0, 0x3fffffc0, v16
	v_lshl_add_u32 v192, v0, 2, s4
	v_lshlrev_b32_e32 v187, 5, v190
	v_or_b32_e32 v0, s86, v191
	v_add_u32_e32 v0, v0, v187
	v_ashrrev_i32_e32 v1, 31, v0
	v_mul_lo_u32 v2, s40, v1
	v_mul_lo_u32 v3, s41, v0
	v_mad_u64_u32 v[0:1], s[4:5], s40, v0, 0
	v_bfe_u32 v189, v16, 5, 1
	v_add3_u32 v1, v1, v2, v3
	v_lshl_add_u64 v[0:1], v[0:1], 1, s[88:89]
	v_lshlrev_b32_e32 v144, 4, v189
	v_ashrrev_i32_e32 v178, 4, v16
	v_lshl_add_u64 v[0:1], v[0:1], 0, v[144:145]
	v_and_b32_e32 v2, 0xfffff0, v178
	v_lshlrev_b32_e32 v3, 1, v178
	global_load_dwordx4 v[124:127], v[0:1], off
	global_load_dwordx4 v[120:123], v[0:1], off offset:32
	global_load_dwordx4 v[116:119], v[0:1], off offset:64
	global_load_dwordx4 v[112:115], v[0:1], off offset:96
	global_load_dwordx4 v[108:111], v[0:1], off offset:128
	global_load_dwordx4 v[104:107], v[0:1], off offset:160
	global_load_dwordx4 v[100:103], v[0:1], off offset:192
	global_load_dwordx4 v[96:99], v[0:1], off offset:224
	v_lshlrev_b32_e32 v0, 3, v16
	v_and_or_b32 v2, v3, 8, v2
	v_and_b32_e32 v1, 0x78, v0
	v_lshrrev_b32_e32 v3, 1, v178
	v_lshrrev_b32_e32 v2, 1, v2
	v_bfe_u32 v0, v0, 5, 2
	v_and_b32_e32 v4, 3, v178
	v_or_b32_e32 v2, v2, v0
	v_and_or_b32 v3, v3, 4, v4
	v_lshlrev_b32_e32 v48, 1, v1
	v_lshlrev_b32_e32 v2, 9, v2
	v_lshlrev_b32_e32 v3, 6, v3
	v_and_b32_e32 v1, 48, v48
	v_add_u32_e32 v18, 32, v178
	v_or3_b32 v17, v2, v3, v1
	v_and_b32_e32 v2, 0xfffff0, v18
	v_lshlrev_b32_e32 v4, 1, v18
	v_and_or_b32 v2, v4, 8, v2
	v_lshrrev_b32_e32 v2, 1, v2
	v_or_b32_e32 v0, v2, v0
	v_and_b32_e32 v186, 63, v16
	v_lshlrev_b32_e32 v0, 9, v0
	v_lshlrev_b32_e32 v188, 4, v16
	v_or3_b32 v19, v0, v3, v1
	v_lshlrev_b32_e32 v0, 3, v186
	v_and_b32_e32 v1, 0xc0, v188
	v_lshlrev_b32_e32 v2, 1, v16
	v_and_or_b32 v1, v0, 24, v1
	v_and_b32_e32 v2, 32, v2
	v_and_b32_e32 v0, 0x100, v0
	s_cselect_b32 s6, 0, 0
	s_ashr_i32 s83, s82, 31
	v_ashrrev_i32_e32 v179, 31, v178
	v_or3_b32 v50, v1, v2, v0
	v_lshl_add_u64 v[0:1], v[178:179], 0, s[82:83]
	v_mul_lo_u32 v2, v1, s40
	v_mul_lo_u32 v3, v0, s41
	v_mad_u64_u32 v[0:1], s[4:5], v0, s40, 0
	v_add3_u32 v1, v1, v3, v2
	v_lshlrev_b64 v[8:9], 1, v[0:1]
	v_lshl_add_u64 v[0:1], s[80:81], 0, v[8:9]
	v_mov_b32_e32 v49, v145
	v_lshl_add_u64 v[0:1], v[0:1], 0, v[48:49]
	v_lshl_add_u64 v[180:181], v[178:179], 0, 32
	global_load_dwordx4 v[0:3], v[0:1], off
	v_lshl_add_u64 v[4:5], v[180:181], 0, s[82:83]
	v_mul_lo_u32 v6, v5, s40
	v_mul_lo_u32 v7, v4, s41
	v_mad_u64_u32 v[4:5], s[4:5], v4, s40, 0
	v_add3_u32 v5, v5, v7, v6
	v_lshlrev_b64 v[12:13], 1, v[4:5]
	v_lshl_add_u64 v[4:5], s[80:81], 0, v[12:13]
	v_lshl_add_u64 v[8:9], s[78:79], 0, v[8:9]
	v_lshl_add_u64 v[12:13], s[78:79], 0, v[12:13]
	v_lshl_add_u64 v[4:5], v[4:5], 0, v[48:49]
	v_lshl_add_u64 v[8:9], v[8:9], 0, v[48:49]
	v_lshl_add_u64 v[12:13], v[12:13], 0, v[48:49]
	global_load_dwordx4 v[4:7], v[4:5], off
	v_add_u32_e32 v195, 0, v17
	global_load_dwordx4 v[8:11], v[8:9], off
	v_lshlrev_b32_e32 v51, 8, v191
	global_load_dwordx4 v[12:15], v[12:13], off
	s_waitcnt vmcnt(0)
	v_and_b32_e32 v60, 0x70, v188
	v_add_u32_e32 v196, 0, v19
	v_or_b32_e32 v52, 32, v144
	v_bitop3_b32 v52, v52, v51, v60 bitop3:0xde
	v_add_u32_e32 v208, 0, v52
	v_readlane_b32 s16, v253, 56
	v_readlane_b32 s17, v253, 57
	v_readlane_b32 s18, v253, 58
	v_readlane_b32 s19, v253, 59
	s_mov_b32 s14, 4
	v_readlane_b32 s20, v253, 60
	v_readlane_b32 s21, v253, 61
	v_readlane_b32 s22, v253, 62
	v_readlane_b32 s23, v253, 63
	v_readlane_b32 s24, v254, 0
	v_readlane_b32 s25, v254, 1
	v_readlane_b32 s26, v254, 2
	v_readlane_b32 s27, v254, 3
	v_readlane_b32 s28, v254, 4
	v_readlane_b32 s29, v254, 5
	v_readlane_b32 s30, v254, 6
	v_readlane_b32 s31, v254, 7
	s_mov_b32 s17, s16
	s_mov_b32 s18, s16
	s_mov_b32 s19, s16
	s_mov_b32 s4, s16
	v_add_u32_e32 v193, s6, v50
	s_mov_b32 s20, s16
	s_mov_b32 s21, s16
	s_mov_b32 s22, s16
	s_mov_b32 s23, s16
	s_mov_b32 s24, s16
	s_mov_b32 s25, s16
	s_mov_b32 s26, s16
	s_mov_b32 s27, s16
	s_mov_b32 s28, s16
	s_mov_b32 s29, s16
	s_mov_b32 s30, s16
	s_mov_b32 s31, s16
	v_writelane_b32 v253, s4, 56
	v_lshl_add_u64 v[182:183], s[80:81], 0, v[48:49]
	v_lshl_add_u64 v[184:185], s[78:79], 0, v[48:49]
	v_writelane_b32 v254, s12, 0
	v_writelane_b32 v254, s13, 1
	v_writelane_b32 v254, s14, 2
	v_writelane_b32 v254, s15, 3
	v_writelane_b32 v254, s16, 4
	v_writelane_b32 v254, s17, 5
	v_writelane_b32 v254, s18, 6
	v_writelane_b32 v254, s19, 7
	v_writelane_b32 v253, s5, 57
	v_writelane_b32 v253, s6, 58
	v_writelane_b32 v253, s7, 59
	v_writelane_b32 v253, s8, 60
	v_writelane_b32 v253, s9, 61
	v_writelane_b32 v253, s10, 62
	v_writelane_b32 v253, s11, 63
	v_lshl_add_u32 v194, v191, 2, v192
	v_mov_b32_e32 v203, 0
	s_waitcnt vmcnt(0)
	ds_write_b128 v195, v[0:3]
	v_lshlrev_b32_e32 v0, 8, v178
	v_and_b32_e32 v1, 0x70, v16
	v_bitop3_b32 v0, v48, v0, v1 bitop3:0xde
	v_add_u32_e32 v198, 0, v0
	v_lshlrev_b32_e32 v0, 8, v18
	v_bitop3_b32 v0, v48, v0, v1 bitop3:0xde
	v_add_u32_e32 v199, 0, v0
	v_bitop3_b32 v0, v144, v51, v60 bitop3:0xde
	v_add_u32_e32 v200, 0, v0
	ds_write_b128 v196, v[4:7]
	ds_write_b128 v198, v[8:11] offset:32768
	ds_write_b128 v199, v[12:15] offset:32768
	s_waitcnt lgkmcnt(0)
	s_barrier
	ds_read_b128 v[16:19], v200 offset:32768
	ds_read_b128 v[20:23], v200 offset:40960
	s_waitcnt lgkmcnt(1)
	v_mfma_f32_32x32x16_bf16 v[32:47], v[16:19], v[124:127], 0
	ds_read_b128 v[52:55], v208 offset:32768
	ds_read_b128 v[56:59], v208 offset:40960
	v_mov_b64_e32 v[0:1], s[16:17]
	v_mov_b64_e32 v[14:15], s[30:31]
	v_mov_b64_e32 v[2:3], s[18:19]
	v_mov_b64_e32 v[4:5], s[20:21]
	v_mov_b64_e32 v[6:7], s[22:23]
	v_mov_b64_e32 v[8:9], s[24:25]
	s_waitcnt lgkmcnt(2)
	v_mfma_f32_32x32x16_bf16 v[16:31], v[20:23], v[124:127], 0
	v_mov_b64_e32 v[10:11], s[26:27]
	v_mov_b64_e32 v[12:13], s[28:29]
	s_waitcnt lgkmcnt(1)
	v_mfma_f32_32x32x16_bf16 v[32:47], v[52:55], v[120:123], v[32:47]
	v_or_b32_e32 v52, 64, v144
	v_bitop3_b32 v52, v52, v51, v60 bitop3:0xde
	v_add_u32_e32 v207, 0, v52
	s_waitcnt lgkmcnt(0)
	v_mfma_f32_32x32x16_bf16 v[16:31], v[56:59], v[120:123], v[16:31]
	ds_read_b128 v[52:55], v207 offset:32768
	ds_read_b128 v[56:59], v207 offset:40960
	s_waitcnt lgkmcnt(1)
	v_mfma_f32_32x32x16_bf16 v[32:47], v[52:55], v[116:119], v[32:47]
	v_or_b32_e32 v52, 0x60, v144
	v_bitop3_b32 v52, v52, v51, v60 bitop3:0xde
	v_add_u32_e32 v206, 0, v52
	s_waitcnt lgkmcnt(0)
	v_mfma_f32_32x32x16_bf16 v[16:31], v[56:59], v[116:119], v[16:31]
	ds_read_b128 v[52:55], v206 offset:32768
	ds_read_b128 v[56:59], v206 offset:40960
	s_waitcnt lgkmcnt(1)
	v_mfma_f32_32x32x16_bf16 v[32:47], v[52:55], v[112:115], v[32:47]
	v_or_b32_e32 v52, 0x80, v144
	v_bitop3_b32 v52, v52, v51, v60 bitop3:0xde
	v_add_u32_e32 v205, 0, v52
	s_waitcnt lgkmcnt(0)
	v_mfma_f32_32x32x16_bf16 v[16:31], v[56:59], v[112:115], v[16:31]
	ds_read_b128 v[52:55], v205 offset:32768
	ds_read_b128 v[56:59], v205 offset:40960
	s_waitcnt lgkmcnt(1)
	v_mfma_f32_32x32x16_bf16 v[32:47], v[52:55], v[108:111], v[32:47]
	v_or_b32_e32 v52, 0xa0, v144
	v_bitop3_b32 v52, v52, v51, v60 bitop3:0xde
	v_add_u32_e32 v204, 0, v52
	s_waitcnt lgkmcnt(0)
	v_mfma_f32_32x32x16_bf16 v[16:31], v[56:59], v[108:111], v[16:31]
	ds_read_b128 v[52:55], v204 offset:32768
	ds_read_b128 v[56:59], v204 offset:40960
	s_waitcnt lgkmcnt(1)
	v_mfma_f32_32x32x16_bf16 v[32:47], v[52:55], v[104:107], v[32:47]
	v_or_b32_e32 v52, 0xc0, v144
	v_bitop3_b32 v52, v52, v51, v60 bitop3:0xde
	v_add_u32_e32 v202, 0, v52
	s_waitcnt lgkmcnt(0)
	v_mfma_f32_32x32x16_bf16 v[16:31], v[56:59], v[104:107], v[16:31]
	ds_read_b128 v[52:55], v202 offset:32768
	ds_read_b128 v[56:59], v202 offset:40960
	s_waitcnt lgkmcnt(1)
	v_mfma_f32_32x32x16_bf16 v[32:47], v[52:55], v[100:103], v[32:47]
	v_or_b32_e32 v52, 0xe0, v144
	v_bitop3_b32 v51, v52, v51, v60 bitop3:0xde
	v_add_u32_e32 v201, 0, v51
	s_waitcnt lgkmcnt(0)
	v_mfma_f32_32x32x16_bf16 v[16:31], v[56:59], v[100:103], v[16:31]
	ds_read_b128 v[52:55], v201 offset:32768
	ds_read_b128 v[56:59], v201 offset:40960
	s_waitcnt lgkmcnt(1)
	v_mfma_f32_32x32x16_bf16 v[32:47], v[52:55], v[96:99], v[32:47]
	s_waitcnt lgkmcnt(0)
	v_mfma_f32_32x32x16_bf16 v[16:31], v[56:59], v[96:99], v[16:31]
	s_nop 9
	v_max_f32_e32 v51, v33, v33
	v_max_f32_e32 v52, v32, v32
	v_max_f32_e32 v51, v52, v51
	v_max3_f32 v51, v51, v34, v35
	v_max3_f32 v51, v51, v36, v37
	v_max3_f32 v51, v51, v38, v39
	v_max3_f32 v51, v51, v40, v41
	v_max3_f32 v51, v51, v42, v43
	v_max3_f32 v51, v51, v44, v45
	v_max3_f32 v51, v51, v46, v47
	v_max3_f32 v51, v51, v16, v17
	v_max3_f32 v51, v51, v18, v19
	v_max3_f32 v51, v51, v20, v21
	v_max3_f32 v51, v51, v22, v23
	v_max3_f32 v51, v51, v24, v25
	v_max3_f32 v51, v51, v26, v27
	v_max3_f32 v51, v51, v28, v29
	v_max3_f32 v51, v51, v30, v31
	v_mov_b32_e32 v52, v51
	s_nop 1
	v_permlane32_swap_b32_e32 v51, v52
	v_max_f32_e32 v52, v52, v52
	v_max_f32_e32 v51, v51, v51
	v_max_f32_e32 v51, v51, v52
	v_add_f32_e32 v52, 0x7149f2ca, v51
	v_max_f32_e32 v51, 0xf149f2ca, v51
	v_cmp_ge_f32_e32 vcc, s93, v52
	v_sub_f32_e32 v52, 0xf149f2ca, v51
	v_mul_f32_e32 v52, 0x3e0293ee, v52
	v_exp_f32_e32 v52, v52
	s_cmp_eq_u64 vcc, exec
	s_cselect_b64 vcc, -1, 0
	v_cndmask_b32_e32 v174, v51, v231, vcc
	s_add_i32 s4, s46, 0x4040
	v_cndmask_b32_e64 v209, v52, 1.0, vcc
	v_mul_f32_e32 v52, 0xbe0293ee, v174
	s_ashr_i32 s5, s4, 31
	v_fma_f32 v150, v20, s92, v52
	v_fma_f32 v151, v21, s92, v52
	v_lshl_add_u64 v[20:21], v[180:181], 0, s[4:5]
	v_fma_f32 v148, v22, s92, v52
	v_fma_f32 v149, v23, s92, v52
	v_fma_f32 v158, v16, s92, v52
	v_fma_f32 v159, v17, s92, v52
	v_lshl_add_u64 v[16:17], v[178:179], 0, s[4:5]
	v_mul_lo_u32 v22, v21, s40
	v_mul_lo_u32 v23, v20, s41
	v_mad_u64_u32 v[20:21], s[4:5], v20, s40, 0
	s_add_i32 s4, s46, 0x4080
	v_fmamk_f32 v32, v32, 0x3e0293ee, v52
	v_fmamk_f32 v33, v33, 0x3e0293ee, v52
	s_ashr_i32 s5, s4, 31
	v_fmamk_f32 v34, v34, 0x3e0293ee, v52
	v_fmamk_f32 v35, v35, 0x3e0293ee, v52
	v_exp_f32_e32 v162, v32
	v_exp_f32_e32 v216, v33
	v_lshl_add_u64 v[32:33], v[178:179], 0, s[4:5]
	v_exp_f32_e32 v163, v34
	v_exp_f32_e32 v177, v35
	v_mul_lo_u32 v34, v33, s40
	v_mul_lo_u32 v35, v32, s41
	v_mad_u64_u32 v[32:33], s[8:9], v32, s40, 0
	v_add3_u32 v33, v33, v35, v34
	v_lshlrev_b64 v[32:33], 1, v[32:33]
	v_lshl_add_u64 v[34:35], s[80:81], 0, v[32:33]
	v_fma_f32 v156, v18, s92, v52
	v_fma_f32 v157, v19, s92, v52
	v_mul_lo_u32 v18, v17, s40
	v_mul_lo_u32 v19, v16, s41
	v_mad_u64_u32 v[16:17], s[8:9], v16, s40, 0
	v_lshl_add_u64 v[34:35], v[34:35], 0, v[48:49]
	v_fmamk_f32 v36, v36, 0x3e0293ee, v52
	v_fmamk_f32 v37, v37, 0x3e0293ee, v52
	v_add3_u32 v17, v17, v19, v18
	global_load_dwordx4 v[128:131], v[34:35], off
	v_lshl_add_u64 v[34:35], v[180:181], 0, s[4:5]
	v_fma_f32 v146, v24, s92, v52
	v_fma_f32 v147, v25, s92, v52
	v_exp_f32_e32 v164, v36
	v_exp_f32_e32 v176, v37
	v_lshlrev_b64 v[24:25], 1, v[16:17]
	v_add3_u32 v21, v21, v23, v22
	v_mul_lo_u32 v36, v35, s40
	v_mul_lo_u32 v37, v34, s41
	v_mad_u64_u32 v[34:35], s[4:5], v34, s40, 0
	v_fma_f32 v154, v28, s92, v52
	v_fma_f32 v155, v29, s92, v52
	v_lshl_add_u64 v[16:17], s[80:81], 0, v[24:25]
	v_lshlrev_b64 v[28:29], 1, v[20:21]
	v_add3_u32 v35, v35, v37, v36
	v_lshl_add_u64 v[32:33], s[78:79], 0, v[32:33]
	v_lshl_add_u64 v[16:17], v[16:17], 0, v[48:49]
	v_lshl_add_u64 v[20:21], s[80:81], 0, v[28:29]
	v_lshlrev_b64 v[34:35], 1, v[34:35]
	v_lshl_add_u64 v[32:33], v[32:33], 0, v[48:49]
	global_load_dwordx4 v[16:19], v[16:17], off
	v_lshl_add_u64 v[20:21], v[20:21], 0, v[48:49]
	v_lshl_add_u64 v[24:25], s[78:79], 0, v[24:25]
	v_lshl_add_u64 v[36:37], s[80:81], 0, v[34:35]
	global_load_dwordx4 v[136:139], v[32:33], off
	v_lshl_add_u64 v[32:33], s[78:79], 0, v[34:35]
	global_load_dwordx4 v[20:23], v[20:21], off
	v_lshl_add_u64 v[24:25], v[24:25], 0, v[48:49]
	v_lshl_add_u64 v[28:29], s[78:79], 0, v[28:29]
	v_lshl_add_u64 v[36:37], v[36:37], 0, v[48:49]
	v_lshl_add_u64 v[32:33], v[32:33], 0, v[48:49]
	v_fma_f32 v160, v26, s92, v52
	v_fma_f32 v161, v27, s92, v52
	global_load_dwordx4 v[24:27], v[24:25], off
	v_lshl_add_u64 v[28:29], v[28:29], 0, v[48:49]
	global_load_dwordx4 v[132:135], v[36:37], off
	global_load_dwordx4 v[140:143], v[32:33], off
	v_fma_f32 v152, v30, s92, v52
	v_fma_f32 v153, v31, s92, v52
	global_load_dwordx4 v[28:31], v[28:29], off
	v_mov_b32_e32 v51, v52
	v_fmamk_f32 v38, v38, 0x3e0293ee, v52
	v_fmamk_f32 v39, v39, 0x3e0293ee, v52
	v_fmamk_f32 v40, v40, 0x3e0293ee, v52
	v_fmamk_f32 v41, v41, 0x3e0293ee, v52
	v_fmamk_f32 v42, v42, 0x3e0293ee, v52
	v_fmamk_f32 v43, v43, 0x3e0293ee, v52
	v_fmamk_f32 v44, v44, 0x3e0293ee, v52
	v_fmamk_f32 v45, v45, 0x3e0293ee, v52
	v_fmamk_f32 v46, v46, 0x3e0293ee, v52
	v_fmac_f32_e32 v51, 0x3e0293ee, v47
	v_exp_f32_e32 v165, v38
	v_exp_f32_e32 v175, v39
	v_exp_f32_e32 v166, v40
	v_exp_f32_e32 v173, v41
	v_exp_f32_e32 v167, v42
	v_exp_f32_e32 v172, v43
	v_exp_f32_e32 v168, v44
	v_exp_f32_e32 v171, v45
	v_exp_f32_e32 v169, v46
	v_exp_f32_e32 v170, v51
	s_waitcnt vmcnt(4)
	s_addk_i32 s6, 0x4000
	s_waitcnt vmcnt(6)
	ds_write_b128 v195, v[16:19] offset:16384
	s_waitcnt vmcnt(4)
	ds_write_b128 v196, v[20:23] offset:16384
	s_waitcnt vmcnt(3)
	ds_write_b128 v198, v[24:27] offset:49152
	s_waitcnt vmcnt(0)
	ds_write_b128 v199, v[28:31] offset:49152
	v_add_u32_e32 v197, s6, v50
	v_mov_b64_e32 v[30:31], v[14:15]
	v_mov_b64_e32 v[46:47], v[14:15]
	v_mov_b64_e32 v[62:63], v[14:15]
	v_cmp_gt_u32_e64 s[4:5], 32, v186
	s_add_i32 s15, s46, 0x40c0
	s_mov_b32 s8, s68
	v_mov_b64_e32 v[28:29], v[12:13]
	v_mov_b64_e32 v[26:27], v[10:11]
	v_mov_b64_e32 v[24:25], v[8:9]
	v_mov_b64_e32 v[22:23], v[6:7]
	v_mov_b64_e32 v[20:21], v[4:5]
	v_mov_b64_e32 v[18:19], v[2:3]
	v_mov_b64_e32 v[16:17], v[0:1]
	v_mov_b64_e32 v[44:45], v[12:13]
	v_mov_b64_e32 v[42:43], v[10:11]
	v_mov_b64_e32 v[40:41], v[8:9]
	v_mov_b64_e32 v[38:39], v[6:7]
	v_mov_b64_e32 v[36:37], v[4:5]
	v_mov_b64_e32 v[34:35], v[2:3]
	v_mov_b64_e32 v[32:33], v[0:1]
	v_mov_b64_e32 v[60:61], v[12:13]
	v_mov_b64_e32 v[58:59], v[10:11]
	v_mov_b64_e32 v[56:57], v[8:9]
	v_mov_b64_e32 v[54:55], v[6:7]
	v_mov_b64_e32 v[52:53], v[4:5]
	v_mov_b64_e32 v[50:51], v[2:3]
	v_mov_b64_e32 v[48:49], v[0:1]
	s_waitcnt lgkmcnt(0)
	s_barrier

.Lgqa_loopA:
	ds_read_b128 v[236:239], v200 offset:49152
	ds_read_b128 v[240:243], v208 offset:49152
	ds_read_b128 v[244:247], v207 offset:49152
	ds_read_b128 v[248:251], v206 offset:49152
	s_add_i32 s6, s14, -3
	s_waitcnt lgkmcnt(3)
	v_mfma_f32_32x32x16_bf16 v[80:95], v[236:239], v[124:127], 0
	ds_read_b128 v[236:239], v205 offset:49152
	v_exp_f32_e32 v162, v162
	v_exp_f32_e32 v216, v216
	v_fma_f32 v158, v64, s92, v152
	v_fma_f32 v159, v65, s92, v152
	s_waitcnt lgkmcnt(3)
	v_mfma_f32_32x32x16_bf16 v[80:95], v[240:243], v[120:123], v[80:95]
	ds_read_b128 v[240:243], v204 offset:49152
	v_exp_f32_e32 v163, v163
	v_exp_f32_e32 v177, v177
	v_fma_f32 v156, v66, s92, v152
	v_fma_f32 v157, v67, s92, v152
	s_waitcnt lgkmcnt(3)
	v_mfma_f32_32x32x16_bf16 v[80:95], v[244:247], v[116:119], v[80:95]
	ds_read_b128 v[244:247], v202 offset:49152
	v_exp_f32_e32 v164, v164
	v_exp_f32_e32 v176, v176
	v_fma_f32 v150, v68, s92, v152
	v_fma_f32 v151, v69, s92, v152
	s_waitcnt lgkmcnt(3)
	v_mfma_f32_32x32x16_bf16 v[80:95], v[248:251], v[112:115], v[80:95]
	ds_read_b128 v[248:251], v201 offset:49152
	v_exp_f32_e32 v165, v165
	v_exp_f32_e32 v175, v175
	v_fma_f32 v148, v70, s92, v152
	v_fma_f32 v149, v71, s92, v152
	s_waitcnt lgkmcnt(3)
	v_mfma_f32_32x32x16_bf16 v[80:95], v[236:239], v[108:111], v[80:95]
	ds_read_b128 v[236:239], v200 offset:57344
	v_exp_f32_e32 v166, v166
	v_exp_f32_e32 v173, v173
	v_fma_f32 v146, v72, s92, v152
	v_fma_f32 v147, v73, s92, v152
	s_waitcnt lgkmcnt(3)
	v_mfma_f32_32x32x16_bf16 v[80:95], v[240:243], v[104:107], v[80:95]
	ds_read_b128 v[240:243], v208 offset:57344
	v_exp_f32_e32 v167, v167
	v_exp_f32_e32 v172, v172
	v_fma_f32 v160, v74, s92, v152
	v_fma_f32 v161, v75, s92, v152
	s_waitcnt lgkmcnt(3)
	v_mfma_f32_32x32x16_bf16 v[80:95], v[244:247], v[100:103], v[80:95]
	ds_read_b128 v[244:247], v207 offset:57344
	v_exp_f32_e32 v168, v168
	v_exp_f32_e32 v171, v171
	v_fma_f32 v154, v76, s92, v152
	v_fma_f32 v155, v77, s92, v152
	s_waitcnt lgkmcnt(3)
	v_mfma_f32_32x32x16_bf16 v[80:95], v[248:251], v[96:99], v[80:95]
	ds_read_b128 v[248:251], v206 offset:57344
	v_exp_f32_e32 v169, v169
	v_exp_f32_e32 v170, v170
	v_fma_f32 v153, v79, s92, v152
	v_fma_f32 v152, v78, s92, v152
	s_waitcnt lgkmcnt(3)
	v_mfma_f32_32x32x16_bf16 v[64:79], v[236:239], v[124:127], 0
	ds_read_b128 v[236:239], v205 offset:57344
	v_exp_f32_e32 v158, v158
	v_exp_f32_e32 v159, v159
	v_add_f32_e32 v210, 0, v162
	s_waitcnt lgkmcnt(3)
	v_mfma_f32_32x32x16_bf16 v[64:79], v[240:243], v[120:123], v[64:79]
	ds_read_b128 v[240:243], v204 offset:57344
	v_exp_f32_e32 v156, v156
	v_exp_f32_e32 v157, v157
	v_add_f32_e32 v210, v216, v210
	s_waitcnt lgkmcnt(3)
	v_mfma_f32_32x32x16_bf16 v[64:79], v[244:247], v[116:119], v[64:79]
	ds_read_b128 v[244:247], v202 offset:57344
	v_exp_f32_e32 v150, v150
	v_exp_f32_e32 v151, v151
	v_add_f32_e32 v210, v163, v210
	s_waitcnt lgkmcnt(3)
	v_mfma_f32_32x32x16_bf16 v[64:79], v[248:251], v[112:115], v[64:79]
	ds_read_b128 v[248:251], v201 offset:57344
	v_exp_f32_e32 v148, v148
	v_exp_f32_e32 v149, v149
	v_add_f32_e32 v210, v177, v210
	s_waitcnt lgkmcnt(3)
	v_mfma_f32_32x32x16_bf16 v[64:79], v[236:239], v[108:111], v[64:79]
	v_exp_f32_e32 v146, v146
	v_exp_f32_e32 v147, v147
	v_add_f32_e32 v210, v164, v210
	s_waitcnt lgkmcnt(2)
	v_mfma_f32_32x32x16_bf16 v[64:79], v[240:243], v[104:107], v[64:79]
	v_exp_f32_e32 v160, v160
	v_exp_f32_e32 v161, v161
	v_add_f32_e32 v210, v176, v210
	s_waitcnt lgkmcnt(1)
	v_mfma_f32_32x32x16_bf16 v[64:79], v[244:247], v[100:103], v[64:79]
	v_exp_f32_e32 v154, v154
	v_exp_f32_e32 v155, v155
	v_add_f32_e32 v210, v165, v210
	s_waitcnt lgkmcnt(0)
	v_mfma_f32_32x32x16_bf16 v[64:79], v[248:251], v[96:99], v[64:79]
	v_exp_f32_e32 v152, v152
	v_exp_f32_e32 v153, v153
	v_add_f32_e32 v210, v175, v210
	s_waitcnt vmcnt(0)
	ds_write_b128 v198, v[136:139] offset:32768
	ds_write_b128 v199, v[140:143] offset:32768
	s_sub_i32 s7, s8, 64
	s_cmp_lt_u32 s6, 2
	s_cselect_b32 s6, s15, s7
	s_ashr_i32 s7, s6, 31
	v_cvt_pk_bf16_f32 v162, v162, v216
	v_cvt_pk_bf16_f32 v163, v163, v177
	v_cvt_pk_bf16_f32 v164, v164, v176
	v_cvt_pk_bf16_f32 v165, v165, v175
	s_nop 0
	v_permlane32_swap_b32_e32 v162, v164
	v_permlane32_swap_b32_e32 v163, v165
	ds_read_b64_tr_b16 v[216:217], v193 offset:0
	ds_read_b64_tr_b16 v[218:219], v193 offset:0x800
	s_waitcnt lgkmcnt(0)
	v_mfma_f32_32x32x16_bf16 v[48:63], v[162:165], v[216:219], v[48:63]
	ds_read_b64_tr_b16 v[220:221], v193 offset:0x1000
	ds_read_b64_tr_b16 v[222:223], v193 offset:0x1800
	ds_read_b64_tr_b16 v[224:225], v193 offset:0x2000
	ds_read_b64_tr_b16 v[226:227], v193 offset:0x2800
	ds_read_b64_tr_b16 v[232:233], v193 offset:0x3000
	ds_read_b64_tr_b16 v[234:235], v193 offset:0x3800
	ds_read_b64_tr_b16 v[216:217], v193 offset:0x200
	ds_read_b64_tr_b16 v[218:219], v193 offset:0xa00
	v_add_f32_e32 v210, v166, v210
	v_add_f32_e32 v210, v173, v210
	v_add_f32_e32 v210, v167, v210
	v_add_f32_e32 v210, v172, v210
	v_add_f32_e32 v210, v168, v210
	v_add_f32_e32 v210, v171, v210
	v_add_f32_e32 v210, v169, v210
	v_cvt_pk_bf16_f32 v166, v166, v173
	v_cvt_pk_bf16_f32 v167, v167, v172
	v_cvt_pk_bf16_f32 v168, v168, v171
	v_cvt_pk_bf16_f32 v169, v169, v170
	s_nop 0
	v_permlane32_swap_b32_e32 v166, v168
	v_permlane32_swap_b32_e32 v167, v169
	s_waitcnt lgkmcnt(6)
	s_nop 0
	v_mfma_f32_32x32x16_bf16 v[48:63], v[166:169], v[220:223], v[48:63]
	ds_read_b64_tr_b16 v[220:221], v193 offset:0x1200
	ds_read_b64_tr_b16 v[222:223], v193 offset:0x1a00
	v_add_f32_e32 v210, v170, v210
	v_add_f32_e32 v210, v158, v210
	v_add_f32_e32 v210, v159, v210
	v_add_f32_e32 v210, v156, v210
	v_add_f32_e32 v210, v157, v210
	v_cvt_pk_bf16_f32 v170, v158, v159
	v_cvt_pk_bf16_f32 v171, v156, v157
	v_cvt_pk_bf16_f32 v172, v150, v151
	v_cvt_pk_bf16_f32 v173, v148, v149
	s_nop 0
	v_permlane32_swap_b32_e32 v170, v172
	v_permlane32_swap_b32_e32 v171, v173
	s_waitcnt lgkmcnt(6)
	s_nop 0
	v_mfma_f32_32x32x16_bf16 v[48:63], v[170:173], v[224:227], v[48:63]
	ds_read_b64_tr_b16 v[224:225], v193 offset:0x2200
	ds_read_b64_tr_b16 v[226:227], v193 offset:0x2a00
	v_add_f32_e32 v210, v150, v210
	v_add_f32_e32 v210, v151, v210
	v_add_f32_e32 v210, v148, v210
	v_add_f32_e32 v210, v149, v210
	v_add_f32_e32 v210, v146, v210
	v_cvt_pk_bf16_f32 v212, v146, v147
	v_cvt_pk_bf16_f32 v213, v160, v161
	v_cvt_pk_bf16_f32 v214, v154, v155
	v_cvt_pk_bf16_f32 v215, v152, v153
	s_nop 0
	v_permlane32_swap_b32_e32 v212, v214
	v_permlane32_swap_b32_e32 v213, v215
	s_waitcnt lgkmcnt(6)
	s_nop 0
	v_mfma_f32_32x32x16_bf16 v[48:63], v[212:215], v[232:235], v[48:63]
	ds_read_b64_tr_b16 v[232:233], v193 offset:0x3200
	ds_read_b64_tr_b16 v[234:235], v193 offset:0x3a00
	v_add_f32_e32 v210, v147, v210
	v_add_f32_e32 v210, v160, v210
	v_add_f32_e32 v210, v161, v210
	v_add_f32_e32 v210, v154, v210
	v_add_f32_e32 v210, v155, v210
	s_waitcnt lgkmcnt(6)
	v_mfma_f32_32x32x16_bf16 v[32:47], v[162:165], v[216:219], v[32:47]
	ds_read_b64_tr_b16 v[216:217], v193 offset:0x400
	ds_read_b64_tr_b16 v[218:219], v193 offset:0xc00
	v_add_f32_e32 v210, v152, v210
	v_add_f32_e32 v210, v153, v210
	v_mov_b32_e32 v211, v210
	s_nop 1
	v_permlane32_swap_b32_e32 v210, v211
	v_lshl_add_u64 v[146:147], s[6:7], 0, v[178:179]
	s_waitcnt lgkmcnt(6)
	v_mfma_f32_32x32x16_bf16 v[32:47], v[166:169], v[220:223], v[32:47]
	ds_read_b64_tr_b16 v[220:221], v193 offset:0x1400
	ds_read_b64_tr_b16 v[222:223], v193 offset:0x1c00
	v_mul_lo_u32 v148, v147, s40
	v_mul_lo_u32 v149, v146, s41
	v_mad_u64_u32 v[146:147], s[10:11], v146, s40, 0
	v_add3_u32 v147, v147, v149, v148
	v_lshl_add_u64 v[148:149], v[180:181], 0, s[6:7]
	v_mul_lo_u32 v150, v149, s40
	v_mul_lo_u32 v151, v148, s41
	v_mad_u64_u32 v[148:149], s[6:7], v148, s40, 0
	v_add3_u32 v149, v149, v151, v150
	v_lshlrev_b64 v[154:155], 1, v[146:147]
	v_lshlrev_b64 v[156:157], 1, v[148:149]
	v_lshl_add_u64 v[146:147], v[182:183], 0, v[154:155]
	global_load_dwordx4 v[146:149], v[146:147], off
	v_lshl_add_u64 v[150:151], v[182:183], 0, v[156:157]
	global_load_dwordx4 v[150:153], v[150:151], off
	v_lshl_add_u64 v[154:155], v[184:185], 0, v[154:155]
	v_lshl_add_u64 v[158:159], v[184:185], 0, v[156:157]
	global_load_dwordx4 v[154:157], v[154:155], off
	global_load_dwordx4 v[158:161], v[158:159], off
	s_waitcnt lgkmcnt(6)
	v_mfma_f32_32x32x16_bf16 v[32:47], v[170:173], v[224:227], v[32:47]
	ds_read_b64_tr_b16 v[224:225], v193 offset:0x2400
	ds_read_b64_tr_b16 v[226:227], v193 offset:0x2c00
	v_max_f32_e32 v250, v81, v81
	v_max_f32_e32 v251, v80, v80
	v_max_f32_e32 v250, v251, v250
	v_max3_f32 v250, v250, v82, v83
	v_max3_f32 v250, v250, v84, v85
	s_waitcnt lgkmcnt(6)
	v_mfma_f32_32x32x16_bf16 v[32:47], v[212:215], v[232:235], v[32:47]
	ds_read_b64_tr_b16 v[232:233], v193 offset:0x3400
	ds_read_b64_tr_b16 v[234:235], v193 offset:0x3c00
	v_max3_f32 v250, v250, v86, v87
	v_max3_f32 v250, v250, v88, v89
	v_max3_f32 v250, v250, v90, v91
	v_max3_f32 v250, v250, v92, v93
	v_max3_f32 v250, v250, v94, v95
	s_waitcnt lgkmcnt(6)
	v_mfma_f32_32x32x16_bf16 v[16:31], v[162:165], v[216:219], v[16:31]
	ds_read_b64_tr_b16 v[216:217], v193 offset:0x600
	ds_read_b64_tr_b16 v[218:219], v193 offset:0xe00
	v_max3_f32 v250, v250, v64, v65
	v_max3_f32 v250, v250, v66, v67
	v_max3_f32 v250, v250, v68, v69
	v_max3_f32 v250, v250, v70, v71
	v_max3_f32 v250, v250, v72, v73
	s_waitcnt lgkmcnt(6)
	v_mfma_f32_32x32x16_bf16 v[16:31], v[166:169], v[220:223], v[16:31]
	ds_read_b64_tr_b16 v[220:221], v193 offset:0x1600
	ds_read_b64_tr_b16 v[222:223], v193 offset:0x1e00
	v_max3_f32 v250, v250, v74, v75
	v_max3_f32 v250, v250, v76, v77
	v_max3_f32 v250, v250, v78, v79
	v_mov_b32_e32 v251, v250
	s_nop 1
	v_permlane32_swap_b32_e32 v250, v251
	s_waitcnt lgkmcnt(6)
	v_mfma_f32_32x32x16_bf16 v[16:31], v[170:173], v[224:227], v[16:31]
	ds_read_b64_tr_b16 v[224:225], v193 offset:0x2600
	ds_read_b64_tr_b16 v[226:227], v193 offset:0x2e00
	v_max_f32_e32 v251, v251, v251
	v_max_f32_e32 v250, v250, v250
	v_max_f32_e32 v250, v250, v251
	v_sub_f32_e32 v251, v250, v174
	v_cmp_ge_f32_e32 vcc, s93, v251
	s_waitcnt lgkmcnt(6)
	v_mfma_f32_32x32x16_bf16 v[16:31], v[212:215], v[232:235], v[16:31]
	ds_read_b64_tr_b16 v[232:233], v193 offset:0x3600
	ds_read_b64_tr_b16 v[234:235], v193 offset:0x3e00
	v_max_f32_e32 v251, v174, v174
	v_max_f32_e32 v250, v251, v250
	v_sub_f32_e32 v251, v174, v250
	v_mul_f32_e32 v251, 0x3e0293ee, v251
	s_waitcnt lgkmcnt(6)
	v_mfma_f32_32x32x16_bf16 v[0:15], v[162:165], v[216:219], v[0:15]
	v_exp_f32_e32 v251, v251
	s_waitcnt lgkmcnt(4)
	v_mfma_f32_32x32x16_bf16 v[0:15], v[166:169], v[220:223], v[0:15]
	s_waitcnt lgkmcnt(2)
	v_mfma_f32_32x32x16_bf16 v[0:15], v[170:173], v[224:227], v[0:15]
	s_waitcnt lgkmcnt(0)
	v_mfma_f32_32x32x16_bf16 v[0:15], v[212:215], v[232:235], v[0:15]
	s_cmp_eq_u64 vcc, exec
	s_cselect_b64 s[6:7], -1, 0

.Lgqa_exit:
	v_exp_f32_e32 v162, v162
	v_exp_f32_e32 v216, v216
	v_exp_f32_e32 v163, v163
	v_exp_f32_e32 v177, v177
	v_exp_f32_e32 v164, v164
	v_exp_f32_e32 v176, v176
	v_exp_f32_e32 v165, v165
	v_exp_f32_e32 v175, v175
	v_exp_f32_e32 v166, v166
	v_exp_f32_e32 v173, v173
	v_exp_f32_e32 v167, v167
	v_exp_f32_e32 v172, v172
	v_exp_f32_e32 v168, v168
	v_exp_f32_e32 v171, v171
	v_exp_f32_e32 v169, v169
	v_exp_f32_e32 v170, v170
	v_fma_f32 v158, v64, s92, v152
	v_fma_f32 v159, v65, s92, v152
	v_fma_f32 v156, v66, s92, v152
	v_fma_f32 v157, v67, s92, v152
	v_fma_f32 v150, v68, s92, v152
	v_fma_f32 v151, v69, s92, v152
	v_fma_f32 v148, v70, s92, v152
	v_fma_f32 v149, v71, s92, v152
	v_fma_f32 v146, v72, s92, v152
	v_fma_f32 v147, v73, s92, v152
	v_fma_f32 v160, v74, s92, v152
	v_fma_f32 v161, v75, s92, v152
	v_fma_f32 v154, v76, s92, v152
	v_fma_f32 v155, v77, s92, v152
	v_fma_f32 v153, v79, s92, v152
	v_fma_f32 v152, v78, s92, v152

.LBB0_761:
	v_mbcnt_lo_u32_b32 v0, -1, 0
	v_mbcnt_hi_u32_b32 v0, -1, v0
	s_add_i32 s4, 0, 0x10000
	v_add_u32_e32 v0, s66, v0
	s_cmp_lg_u32 0, -1
	v_ashrrev_i32_e32 v178, 6, v0
	v_and_b32_e32 v179, 31, v0
	v_lshlrev_b32_e32 v175, 5, v178
	v_or_b32_e32 v2, s86, v179
	v_add_u32_e32 v2, v2, v175
	v_and_b32_e32 v1, 0x3fffffc0, v0
	v_ashrrev_i32_e32 v3, 31, v2
	v_lshl_add_u32 v180, v1, 2, s4
	v_mul_lo_u32 v4, s40, v3
	v_mul_lo_u32 v5, s41, v2
	v_mad_u64_u32 v[2:3], s[4:5], s40, v2, 0
	v_add3_u32 v3, v3, v4, v5
	v_bfe_u32 v177, v0, 5, 1
	v_lshlrev_b64 v[2:3], 1, v[2:3]
	v_lshl_add_u64 v[4:5], s[88:89], 0, v[2:3]
	v_lshlrev_b32_e32 v144, 4, v177
	v_lshl_add_u64 v[2:3], s[72:73], 0, v[2:3]
	v_lshl_add_u64 v[4:5], v[4:5], 0, v[144:145]
	v_lshl_add_u64 v[6:7], v[2:3], 0, v[144:145]
	global_load_dwordx4 v[124:127], v[4:5], off
	global_load_dwordx4 v[120:123], v[4:5], off offset:32
	global_load_dwordx4 v[116:119], v[4:5], off offset:64
	global_load_dwordx4 v[112:115], v[4:5], off offset:96
	global_load_dwordx4 v[108:111], v[4:5], off offset:128
	global_load_dwordx4 v[104:107], v[4:5], off offset:160
	global_load_dwordx4 v[100:103], v[4:5], off offset:192
	global_load_dwordx4 v[96:99], v[4:5], off offset:224
	v_and_b32_e32 v174, 63, v0
	global_load_dwordx4 v[2:5], v[6:7], off
	v_lshl_add_u32 v1, v178, 12, s53
	v_lshlrev_b32_e32 v8, 4, v174
	v_add_u32_e32 v182, v1, v8
	v_ashrrev_i32_e32 v162, 4, v0
	v_lshlrev_b32_e32 v56, 3, v0
	v_and_b32_e32 v1, 0x78, v56
	v_lshlrev_b32_e32 v48, 1, v1
	v_and_b32_e32 v1, 48, v48
	v_add_u32_e32 v23, 32, v162
	v_ashrrev_i32_e32 v163, 31, v162
	s_cselect_b32 s6, 0, 0
	s_ashr_i32 s83, s82, 31
	v_lshl_add_u64 v[166:167], v[162:163], 0, 32
	v_ashrrev_i32_e32 v164, 3, v0
	v_ashrrev_i32_e32 v165, 31, v164
	v_lshl_add_u64 v[18:19], v[164:165], 0, s[82:83]
	v_mov_b64_e32 v[52:53], s[0:1]
	v_mad_u64_u32 v[20:21], s[4:5], v18, s3, v[52:53]
	v_lshlrev_b32_e32 v176, 4, v0
	v_mov_b32_e32 v49, v145
	v_mad_i32_i24 v21, v19, s3, v21
	v_and_b32_e32 v50, 0x70, v176
	v_mov_b32_e32 v51, v145
	v_lshl_add_u64 v[18:19], v[20:21], 0, v[50:51]
	global_load_dwordx4 v[18:21], v[18:19], off
	v_lshlrev_b32_e32 v57, 8, v179
	v_or_b32_e32 v68, 32, v144
	v_bitop3_b32 v58, v68, v57, v50 bitop3:0xde
	v_add_u32_e32 v191, 0, v58
	v_or_b32_e32 v69, 64, v144
	v_or_b32_e32 v70, 0x60, v144
	v_lshlrev_b32_e32 v71, 7, v179
	v_and_b32_e32 v72, 0x70, v56
	v_bitop3_b32 v198, v144, v71, v72 bitop3:0xde
	v_bitop3_b32 v200, v68, v71, v72 bitop3:0xde
	v_bitop3_b32 v202, v69, v71, v72 bitop3:0xde
	v_bitop3_b32 v204, v70, v71, v72 bitop3:0xde
	s_mov_b32 s8, 0
	s_mov_b32 s9, s8
	s_mov_b32 s10, s8
	s_mov_b32 s11, s8
	s_mov_b32 s12, s8
	s_mov_b32 s13, s8
	s_mov_b32 s14, s8
	s_mov_b32 s15, s8
	s_mov_b32 s16, s8
	s_mov_b32 s17, s8
	s_mov_b32 s18, s8
	s_mov_b32 s19, s8
	s_mov_b32 s20, s8
	s_mov_b32 s21, s8
	s_mov_b32 s22, s8
	s_mov_b32 s23, s8
	v_lshl_add_u64 v[168:169], s[80:81], 0, v[48:49]
	v_lshl_add_u64 v[170:171], s[78:79], 0, v[48:49]
	v_lshl_add_u64 v[172:173], s[0:1], 0, v[50:51]
	s_mov_b32 s24, 2
	v_lshl_add_u32 v183, v179, 2, v180
	v_mov_b32_e32 v197, 0
	s_waitcnt vmcnt(0)
	ds_write_b128 v182, v[2:5]
	global_load_dwordx4 v[2:5], v[6:7], off offset:32
	s_waitcnt vmcnt(0)
	ds_write_b128 v182, v[2:5] offset:1024
	global_load_dwordx4 v[2:5], v[6:7], off offset:64
	s_waitcnt vmcnt(0)
	ds_write_b128 v182, v[2:5] offset:2048
	global_load_dwordx4 v[2:5], v[6:7], off offset:96
	v_lshl_add_u64 v[6:7], v[166:167], 0, s[82:83]
	v_mul_lo_u32 v9, v6, s41
	s_waitcnt vmcnt(0)
	ds_write_b128 v182, v[2:5] offset:3072
	v_and_b32_e32 v2, 0xfffff0, v162
	v_lshlrev_b32_e32 v3, 1, v162
	v_and_or_b32 v2, v3, 8, v2
	v_lshrrev_b32_e32 v3, 1, v162
	v_lshrrev_b32_e32 v2, 1, v2
	v_bfe_u32 v4, v56, 5, 2
	v_and_b32_e32 v5, 3, v162
	v_or_b32_e32 v2, v2, v4
	v_and_or_b32 v3, v3, 4, v5
	v_lshlrev_b32_e32 v2, 9, v2
	v_lshlrev_b32_e32 v3, 6, v3
	v_or3_b32 v22, v2, v3, v1
	v_and_b32_e32 v2, 0xfffff0, v23
	v_lshlrev_b32_e32 v5, 1, v23
	v_and_or_b32 v2, v5, 8, v2
	v_lshrrev_b32_e32 v2, 1, v2
	v_or_b32_e32 v2, v2, v4
	v_lshlrev_b32_e32 v2, 9, v2
	v_or3_b32 v1, v2, v3, v1
	v_lshlrev_b32_e32 v2, 3, v174
	v_and_b32_e32 v3, 0xc0, v8
	v_lshlrev_b32_e32 v4, 1, v0
	v_and_or_b32 v3, v2, 24, v3
	v_and_b32_e32 v4, 32, v4
	v_and_b32_e32 v2, 0x100, v2
	v_or3_b32 v54, v3, v4, v2
	v_lshl_add_u64 v[2:3], v[162:163], 0, s[82:83]
	v_mul_lo_u32 v4, v3, s40
	v_mul_lo_u32 v5, v2, s41
	v_mad_u64_u32 v[2:3], s[4:5], v2, s40, 0
	v_mul_lo_u32 v8, v7, s40
	v_mad_u64_u32 v[6:7], s[4:5], v6, s40, 0
	v_add3_u32 v3, v3, v5, v4
	v_add3_u32 v7, v7, v9, v8
	v_lshlrev_b64 v[10:11], 1, v[2:3]
	v_lshlrev_b64 v[14:15], 1, v[6:7]
	v_lshl_add_u64 v[2:3], s[80:81], 0, v[10:11]
	v_lshl_add_u64 v[6:7], s[80:81], 0, v[14:15]
	v_lshl_add_u64 v[10:11], s[78:79], 0, v[10:11]
	v_lshl_add_u64 v[14:15], s[78:79], 0, v[14:15]
	v_lshl_add_u64 v[2:3], v[2:3], 0, v[48:49]
	v_lshl_add_u64 v[6:7], v[6:7], 0, v[48:49]
	v_lshl_add_u64 v[10:11], v[10:11], 0, v[48:49]
	v_lshl_add_u64 v[14:15], v[14:15], 0, v[48:49]
	global_load_dwordx4 v[2:5], v[2:3], off
	v_add_u32_e32 v186, 0, v1
	global_load_dwordx4 v[6:9], v[6:7], off
	v_lshlrev_b32_e32 v1, 8, v162
	global_load_dwordx4 v[10:13], v[10:11], off
	v_and_b32_e32 v0, 0x70, v0
	global_load_dwordx4 v[14:17], v[14:15], off
	v_bitop3_b32 v1, v48, v1, v0 bitop3:0xde
	v_add_u32_e32 v187, 0, v1
	v_lshlrev_b32_e32 v1, 8, v23
	v_bitop3_b32 v1, v48, v1, v0 bitop3:0xde
	v_add_u32_e32 v188, 0, v1
	v_lshlrev_b32_e32 v1, 7, v164
	v_bitop3_b32 v55, v50, v1, v0 bitop3:0xde
	s_add_i32 s4, 0, 0x10800
	v_add_u32_e32 v185, 0, v22
	v_add_u32_e32 v0, s4, v55
	s_waitcnt vmcnt(0)
	v_add_u32_e32 v199, s4, v198
	v_add_u32_e32 v201, s4, v200
	v_add_u32_e32 v203, s4, v202
	v_add_u32_e32 v205, s4, v204
	v_add_u32_e32 v208, 0, v55
	v_add_u32_e32 v181, s6, v54
	v_add_u32_e32 v209, 0x12800, v208
	s_waitcnt vmcnt(3)
	ds_write_b128 v185, v[2:5]
	s_waitcnt vmcnt(2)
	ds_write_b128 v186, v[6:9]
	s_waitcnt vmcnt(1)
	ds_write_b128 v187, v[10:13] offset:32768
	s_waitcnt vmcnt(0)
	ds_write_b128 v188, v[14:17] offset:32768
	ds_write_b128 v0, v[18:21]
	v_bitop3_b32 v0, v144, v57, v50 bitop3:0xde
	v_add_u32_e32 v189, 0, v0
	s_waitcnt lgkmcnt(0)
	s_barrier
	ds_read_b128 v[16:19], v189 offset:32768
	ds_read_b128 v[20:23], v189 offset:40960
	s_waitcnt lgkmcnt(1)
	v_mfma_f32_32x32x16_bf16 v[32:47], v[16:19], v[124:127], 0
	ds_read_b128 v[58:61], v191 offset:32768
	ds_read_b128 v[62:65], v191 offset:40960
	v_mov_b64_e32 v[0:1], s[8:9]
	v_mov_b64_e32 v[2:3], s[10:11]
	v_mov_b64_e32 v[4:5], s[12:13]
	v_mov_b64_e32 v[6:7], s[14:15]
	v_mov_b64_e32 v[8:9], s[16:17]
	v_mov_b64_e32 v[10:11], s[18:19]
	s_waitcnt lgkmcnt(2)
	v_mfma_f32_32x32x16_bf16 v[16:31], v[20:23], v[124:127], 0
	v_mov_b64_e32 v[12:13], s[20:21]
	v_mov_b64_e32 v[14:15], s[22:23]
	s_waitcnt lgkmcnt(1)
	v_mfma_f32_32x32x16_bf16 v[32:47], v[58:61], v[120:123], v[32:47]
	v_bitop3_b32 v58, v69, v57, v50 bitop3:0xde
	v_add_u32_e32 v193, 0, v58
	s_waitcnt lgkmcnt(0)
	v_mfma_f32_32x32x16_bf16 v[16:31], v[62:65], v[120:123], v[16:31]
	ds_read_b128 v[58:61], v193 offset:32768
	ds_read_b128 v[62:65], v193 offset:40960
	s_waitcnt lgkmcnt(1)
	v_mfma_f32_32x32x16_bf16 v[32:47], v[58:61], v[116:119], v[32:47]
	v_bitop3_b32 v58, v70, v57, v50 bitop3:0xde
	v_add_u32_e32 v195, 0, v58
	s_waitcnt lgkmcnt(0)
	v_mfma_f32_32x32x16_bf16 v[16:31], v[62:65], v[116:119], v[16:31]
	ds_read_b128 v[58:61], v195 offset:32768
	ds_read_b128 v[62:65], v195 offset:40960
	s_waitcnt lgkmcnt(1)
	v_mfma_f32_32x32x16_bf16 v[32:47], v[58:61], v[112:115], v[32:47]
	v_or_b32_e32 v58, 0x80, v144
	v_bitop3_b32 v58, v58, v57, v50 bitop3:0xde
	v_add_u32_e32 v196, 0, v58
	s_waitcnt lgkmcnt(0)
	v_mfma_f32_32x32x16_bf16 v[16:31], v[62:65], v[112:115], v[16:31]
	ds_read_b128 v[58:61], v196 offset:32768
	ds_read_b128 v[62:65], v196 offset:40960
	s_waitcnt lgkmcnt(1)
	v_mfma_f32_32x32x16_bf16 v[32:47], v[58:61], v[108:111], v[32:47]
	v_or_b32_e32 v58, 0xa0, v144
	v_bitop3_b32 v58, v58, v57, v50 bitop3:0xde
	v_add_u32_e32 v194, 0, v58
	s_waitcnt lgkmcnt(0)
	v_mfma_f32_32x32x16_bf16 v[16:31], v[62:65], v[108:111], v[16:31]
	ds_read_b128 v[58:61], v194 offset:32768
	ds_read_b128 v[62:65], v194 offset:40960
	s_waitcnt lgkmcnt(1)
	v_mfma_f32_32x32x16_bf16 v[32:47], v[58:61], v[104:107], v[32:47]
	v_or_b32_e32 v58, 0xc0, v144
	v_bitop3_b32 v58, v58, v57, v50 bitop3:0xde
	v_add_u32_e32 v192, 0, v58
	s_waitcnt lgkmcnt(0)
	v_mfma_f32_32x32x16_bf16 v[16:31], v[62:65], v[104:107], v[16:31]
	ds_read_b128 v[58:61], v192 offset:32768
	ds_read_b128 v[62:65], v192 offset:40960
	s_waitcnt lgkmcnt(1)
	v_mfma_f32_32x32x16_bf16 v[32:47], v[58:61], v[100:103], v[32:47]
	v_or_b32_e32 v58, 0xe0, v144
	v_bitop3_b32 v57, v58, v57, v50 bitop3:0xde
	v_add_u32_e32 v190, 0, v57
	s_waitcnt lgkmcnt(0)
	v_mfma_f32_32x32x16_bf16 v[16:31], v[62:65], v[100:103], v[16:31]
	ds_read_b128 v[58:61], v190 offset:32768
	ds_read_b128 v[62:65], v190 offset:40960
	s_waitcnt lgkmcnt(1)
	v_mfma_f32_32x32x16_bf16 v[32:47], v[58:61], v[96:99], v[32:47]
	s_waitcnt lgkmcnt(0)
	v_mfma_f32_32x32x16_bf16 v[16:31], v[62:65], v[96:99], v[16:31]
	ds_read_b128 v[56:59], v199
	ds_read_b128 v[60:63], v199 offset:4096
	ds_read_b128 v[64:67], v182
	s_waitcnt lgkmcnt(0)
	v_mfma_f32_32x32x16_bf16 v[32:47], v[56:59], v[64:67], v[32:47]
	v_mfma_f32_32x32x16_bf16 v[16:31], v[60:63], v[64:67], v[16:31]
	ds_read_b128 v[56:59], v201
	ds_read_b128 v[60:63], v201 offset:4096
	ds_read_b128 v[64:67], v182 offset:1024
	s_waitcnt lgkmcnt(0)
	v_mfma_f32_32x32x16_bf16 v[32:47], v[56:59], v[64:67], v[32:47]
	v_mfma_f32_32x32x16_bf16 v[16:31], v[60:63], v[64:67], v[16:31]
	ds_read_b128 v[56:59], v203
	ds_read_b128 v[60:63], v203 offset:4096
	ds_read_b128 v[64:67], v182 offset:2048
	s_waitcnt lgkmcnt(0)
	v_mfma_f32_32x32x16_bf16 v[32:47], v[56:59], v[64:67], v[32:47]
	v_mfma_f32_32x32x16_bf16 v[16:31], v[60:63], v[64:67], v[16:31]
	ds_read_b128 v[56:59], v205
	ds_read_b128 v[60:63], v205 offset:4096
	ds_read_b128 v[64:67], v182 offset:3072
	s_waitcnt lgkmcnt(0)
	v_mfma_f32_32x32x16_bf16 v[32:47], v[56:59], v[64:67], v[32:47]
	v_mfma_f32_32x32x16_bf16 v[16:31], v[60:63], v[64:67], v[16:31]
	s_nop 10
	v_max_f32_e32 v56, v33, v33
	v_max_f32_e32 v57, v32, v32
	v_max_f32_e32 v56, v57, v56
	v_max3_f32 v56, v56, v34, v35
	v_max3_f32 v56, v56, v36, v37
	v_max3_f32 v56, v56, v38, v39
	v_max3_f32 v56, v56, v40, v41
	v_max3_f32 v56, v56, v42, v43
	v_max3_f32 v56, v56, v44, v45
	v_max3_f32 v56, v56, v46, v47
	v_max3_f32 v56, v56, v16, v17
	v_max3_f32 v56, v56, v18, v19
	v_max3_f32 v56, v56, v20, v21
	v_max3_f32 v56, v56, v22, v23
	v_max3_f32 v56, v56, v24, v25
	v_max3_f32 v56, v56, v26, v27
	v_max3_f32 v56, v56, v28, v29
	v_max3_f32 v56, v56, v30, v31
	v_mov_b32_e32 v57, v56
	s_nop 1
	v_permlane32_swap_b32_e32 v56, v57
	v_max_f32_e32 v57, v57, v57
	v_max_f32_e32 v56, v56, v56
	v_max_f32_e32 v56, v56, v57
	v_add_f32_e32 v57, 0x7149f2ca, v56
	v_max_f32_e32 v56, 0xf149f2ca, v56
	v_cmp_ge_f32_e32 vcc, s94, v57
	v_sub_f32_e32 v57, 0xf149f2ca, v56
	v_mul_f32_e32 v57, 0x3dd53b94, v57
	s_cmp_eq_u64 vcc, exec
	v_exp_f32_e32 v57, v57
	s_cselect_b64 vcc, -1, 0
	v_cndmask_b32_e32 v207, v56, v231, vcc
	v_mul_f32_e32 v56, 0xbdd53b94, v207
	v_cndmask_b32_e64 v206, v57, 1.0, vcc
	v_mov_b32_e32 v57, v56
	s_add_i32 s4, s46, 0x4040
	v_fmac_f32_e32 v57, 0x3dd53b94, v47
	s_ashr_i32 s5, s4, 31
	v_fma_f32 v140, v16, s76, v56
	v_fma_f32 v141, v17, s76, v56
	v_lshl_add_u64 v[16:17], v[162:163], 0, s[4:5]
	v_fmamk_f32 v32, v32, 0x3dd53b94, v56
	v_fmamk_f32 v33, v33, 0x3dd53b94, v56
	v_fma_f32 v132, v20, s76, v56
	v_fma_f32 v133, v21, s76, v56
	v_fma_f32 v138, v18, s76, v56
	v_fma_f32 v139, v19, s76, v56
	v_mul_lo_u32 v18, v17, s40
	v_mul_lo_u32 v19, v16, s41
	v_mad_u64_u32 v[16:17], s[10:11], v16, s40, 0
	v_lshl_add_u64 v[20:21], v[166:167], 0, s[4:5]
	v_fmamk_f32 v34, v34, 0x3dd53b94, v56
	v_fmamk_f32 v35, v35, 0x3dd53b94, v56
	v_fma_f32 v130, v22, s76, v56
	v_fma_f32 v131, v23, s76, v56
	v_exp_f32_e32 v159, v32
	v_exp_f32_e32 v161, v33
	v_add3_u32 v17, v17, v19, v18
	v_mul_lo_u32 v22, v21, s40
	v_mul_lo_u32 v23, v20, s41
	v_mad_u64_u32 v[20:21], s[10:11], v20, s40, 0
	v_lshl_add_u64 v[32:33], v[164:165], 0, s[4:5]
	v_fma_f32 v128, v24, s76, v56
	v_fma_f32 v129, v25, s76, v56
	v_exp_f32_e32 v157, v34
	v_exp_f32_e32 v160, v35
	v_lshlrev_b64 v[24:25], 1, v[16:17]
	v_add3_u32 v21, v21, v23, v22
	v_mad_u64_u32 v[34:35], s[4:5], v32, s3, v[52:53]
	v_fma_f32 v136, v28, s76, v56
	v_fma_f32 v137, v29, s76, v56
	v_lshl_add_u64 v[16:17], s[80:81], 0, v[24:25]
	v_lshlrev_b64 v[28:29], 1, v[20:21]
	v_mad_i32_i24 v35, v33, s3, v35
	v_lshl_add_u64 v[16:17], v[16:17], 0, v[48:49]
	v_lshl_add_u64 v[20:21], s[80:81], 0, v[28:29]
	v_lshl_add_u64 v[32:33], v[34:35], 0, v[50:51]
	global_load_dwordx4 v[16:19], v[16:17], off
	v_lshl_add_u64 v[20:21], v[20:21], 0, v[48:49]
	v_lshl_add_u64 v[24:25], s[78:79], 0, v[24:25]
	global_load_dwordx4 v[32:35], v[32:33], off
	v_lshl_add_u64 v[24:25], v[24:25], 0, v[48:49]
	global_load_dwordx4 v[20:23], v[20:21], off
	v_lshl_add_u64 v[28:29], s[78:79], 0, v[28:29]
	v_fma_f32 v142, v26, s76, v56
	v_fma_f32 v143, v27, s76, v56
	global_load_dwordx4 v[24:27], v[24:25], off
	v_lshl_add_u64 v[28:29], v[28:29], 0, v[48:49]
	v_fma_f32 v134, v30, s76, v56
	v_fma_f32 v135, v31, s76, v56
	global_load_dwordx4 v[28:31], v[28:29], off
	v_fmamk_f32 v36, v36, 0x3dd53b94, v56
	v_fmamk_f32 v37, v37, 0x3dd53b94, v56
	v_fmamk_f32 v38, v38, 0x3dd53b94, v56
	v_fmamk_f32 v39, v39, 0x3dd53b94, v56
	v_fmamk_f32 v40, v40, 0x3dd53b94, v56
	v_fmamk_f32 v41, v41, 0x3dd53b94, v56
	v_fmamk_f32 v42, v42, 0x3dd53b94, v56
	v_fmamk_f32 v43, v43, 0x3dd53b94, v56
	v_fmamk_f32 v44, v44, 0x3dd53b94, v56
	v_fmamk_f32 v45, v45, 0x3dd53b94, v56
	v_fmamk_f32 v46, v46, 0x3dd53b94, v56
	v_exp_f32_e32 v156, v36
	v_exp_f32_e32 v158, v37
	v_exp_f32_e32 v154, v38
	v_exp_f32_e32 v155, v39
	v_exp_f32_e32 v151, v40
	v_exp_f32_e32 v153, v41
	v_exp_f32_e32 v150, v42
	v_exp_f32_e32 v152, v43
	v_exp_f32_e32 v147, v44
	v_exp_f32_e32 v149, v45
	v_exp_f32_e32 v146, v46
	v_exp_f32_e32 v148, v57
	s_waitcnt vmcnt(0)
	s_addk_i32 s6, 0x4000
	s_waitcnt vmcnt(4)
	ds_write_b128 v185, v[16:19] offset:16384
	s_waitcnt vmcnt(2)
	ds_write_b128 v186, v[20:23] offset:16384
	s_waitcnt vmcnt(1)
	ds_write_b128 v187, v[24:27] offset:49152
	s_waitcnt vmcnt(0)
	ds_write_b128 v188, v[28:31] offset:49152
	ds_write_b128 v209, v[32:35]
	v_add_u32_e32 v184, s6, v54
	v_mov_b64_e32 v[62:63], v[14:15]
	v_mov_b64_e32 v[46:47], v[14:15]
	v_mov_b64_e32 v[30:31], v[14:15]
	v_cmp_gt_u32_e64 s[4:5], 32, v174
	s_addk_i32 s46, 0x4080
	s_addk_i32 s68, 0xff80
	v_mov_b64_e32 v[60:61], v[12:13]
	v_mov_b64_e32 v[58:59], v[10:11]
	v_mov_b64_e32 v[56:57], v[8:9]
	v_mov_b64_e32 v[54:55], v[6:7]
	v_mov_b64_e32 v[52:53], v[4:5]
	v_mov_b64_e32 v[50:51], v[2:3]
	v_mov_b64_e32 v[48:49], v[0:1]
	v_mov_b64_e32 v[44:45], v[12:13]
	v_mov_b64_e32 v[42:43], v[10:11]
	v_mov_b64_e32 v[40:41], v[8:9]
	v_mov_b64_e32 v[38:39], v[6:7]
	v_mov_b64_e32 v[36:37], v[4:5]
	v_mov_b64_e32 v[34:35], v[2:3]
	v_mov_b64_e32 v[32:33], v[0:1]
	v_mov_b64_e32 v[28:29], v[12:13]
	v_mov_b64_e32 v[26:27], v[10:11]
	v_mov_b64_e32 v[24:25], v[8:9]
	v_mov_b64_e32 v[22:23], v[6:7]
	v_mov_b64_e32 v[20:21], v[4:5]
	v_mov_b64_e32 v[18:19], v[2:3]
	v_mov_b64_e32 v[16:17], v[0:1]
	s_waitcnt lgkmcnt(0)
	s_barrier

.LBB0_770:
	v_cndmask_b32_e64 v207, v250, v207, s[6:7]
	v_mul_f32_e32 v134, 0xbdd53b94, v207
	v_mov_b32_e32 v135, v134
	v_fmamk_f32 v80, v80, 0x3dd53b94, v134
	v_fmamk_f32 v81, v81, 0x3dd53b94, v134
	v_fmamk_f32 v82, v82, 0x3dd53b94, v134
	v_fmamk_f32 v83, v83, 0x3dd53b94, v134
	v_fmamk_f32 v84, v84, 0x3dd53b94, v134
	v_fmamk_f32 v85, v85, 0x3dd53b94, v134
	v_fmamk_f32 v86, v86, 0x3dd53b94, v134
	v_fmamk_f32 v87, v87, 0x3dd53b94, v134
	v_fmamk_f32 v88, v88, 0x3dd53b94, v134
	v_fmamk_f32 v89, v89, 0x3dd53b94, v134
	v_fmamk_f32 v90, v90, 0x3dd53b94, v134
	v_fmamk_f32 v91, v91, 0x3dd53b94, v134
	v_fmamk_f32 v92, v92, 0x3dd53b94, v134
	v_fmamk_f32 v93, v93, 0x3dd53b94, v134
	v_fmamk_f32 v94, v94, 0x3dd53b94, v134
	v_fmac_f32_e32 v135, 0x3dd53b94, v95
	v_exp_f32_e32 v159, v80
	v_exp_f32_e32 v161, v81
	v_exp_f32_e32 v157, v82
	v_exp_f32_e32 v160, v83
	v_exp_f32_e32 v156, v84
	v_exp_f32_e32 v158, v85
	v_exp_f32_e32 v154, v86
	v_exp_f32_e32 v155, v87
	v_exp_f32_e32 v151, v88
	v_exp_f32_e32 v153, v89
	v_exp_f32_e32 v150, v90
	v_exp_f32_e32 v152, v91
	v_exp_f32_e32 v147, v92
	v_exp_f32_e32 v149, v93
	v_exp_f32_e32 v146, v94
	v_exp_f32_e32 v148, v135
	v_fma_f32 v140, v64, s76, v134
	v_fma_f32 v141, v65, s76, v134
	v_add_f32_e32 v64, v218, v219
	v_fmac_f32_e32 v64, v206, v197
	v_add_f32_e32 v197, v222, v223
	s_addk_i32 s8, 0x80
	s_add_i32 s24, s24, 2
	v_fma_f32 v138, v66, s76, v134
	v_fma_f32 v139, v67, s76, v134
	v_fma_f32 v132, v68, s76, v134
	v_fma_f32 v133, v69, s76, v134
	v_fma_f32 v130, v70, s76, v134
	v_fma_f32 v131, v71, s76, v134
	v_fma_f32 v128, v72, s76, v134
	v_fma_f32 v129, v73, s76, v134
	v_fma_f32 v142, v74, s76, v134
	v_fma_f32 v143, v75, s76, v134
	v_fma_f32 v136, v76, s76, v134
	v_fma_f32 v137, v77, s76, v134
	v_fma_f32 v135, v79, s76, v134
	v_fma_f32 v134, v78, s76, v134
	v_fmac_f32_e32 v197, v64, v220
	s_cmp_ge_u32 s24, s91
	s_waitcnt lgkmcnt(2)
	s_barrier
	s_cbranch_scc1 .LBB0_772
	v_mov_b32_e32 v206, v221
	s_branch .LBB0_762
